# LRU: hoist + double-buffered uc tile + clamp trim combined
# speedup vs baseline: 1.0044x; 1.0017x over previous
; __device__ __forceinline__ float bf2f(u16 h) { return __uint_as_float(((unsigned)h) << 16); }
; __device__ __forceinline__ void lru_tile(const Params& P, int chunk, int head, int pass, char* smem_raw) {
;     ...
;         const bf16x8 af = *reinterpret_cast<const bf16x8*>(&sm_uc[(sb * 64 + wid * 16 + (lane & 15)) * LDSS + s * 32 + (lane >> 4) * 8]);
; #pragma unroll
;         for (int t = 0; t < 8; ++t) {
;           const bf16x8 bfr = *reinterpret_cast<const bf16x8*>(&sm_w[(t * 16 + (lane & 15)) * LDSS + s * 32 + (lane >> 4) * 8]);
;           acc[t] = __builtin_amdgcn_mfma_f32_16x16x32_bf16(af, bfr, acc[t], 0, 0, 0);
;         }
;       }
; #pragma unroll
;       for (int tc = 0; tc < 4; ++tc)
; #pragma unroll
;         for (int reg = 0; reg < 4; ++reg) {
;           const int tl = wid * 16 + (lane >> 4) * 4 + reg;
;           const int c = 16 * tc + (lane & 15);
;           const float r = __builtin_amdgcn_rcpf(1.f + __builtin_amdgcn_exp2f(acc[tc][reg] + ba[tc]));
;           const float ii = __builtin_amdgcn_rcpf(1.f + __builtin_amdgcn_exp2f(acc[tc + 4][reg] + bi[tc]));
;           const float la = -c8[tc] * r;
;           const float a = __builtin_amdgcn_exp2f(la);
;           const float ucv = bf2f(sm_uc[(sb * 64 + tl) * LDSS + c]);
;           const float bt = __builtin_amdgcn_sqrtf(fmaxf(1.f - a * a, 0.f)) * (ii * ucv);
;           sm_a[tl * 64 + c] = a;
;           sm_b[tl * 64 + c] = bt;
;         }
.Lmy_lrua_nopf:
	ds_read_b128 v[76:79], v131 offset:0
	ds_read_b128 v[80:83], v133 offset:0
	ds_read_b128 v[122:125], v131 offset:512
	ds_read_b128 v[126:129], v133 offset:512
	s_waitcnt lgkmcnt(3)
	v_mfma_f32_16x16x32_bf16 v[0:3], v[76:79], v[238:241], 0
	v_mfma_f32_16x16x32_bf16 v[90:93], v[76:79], v[246:249], 0
	ds_read_b128 v[76:79], v131 offset:1024
	s_waitcnt lgkmcnt(3)
	v_mfma_f32_16x16x32_bf16 v[0:3], v[80:83], v[242:245], v[0:3]
	v_mfma_f32_16x16x32_bf16 v[90:93], v[80:83], v[194:197], v[90:93]
	ds_read_b128 v[80:83], v133 offset:1024
	s_waitcnt lgkmcnt(3)
	v_mfma_f32_16x16x32_bf16 v[4:7], v[122:125], v[238:241], 0
	v_mfma_f32_16x16x32_bf16 v[94:97], v[122:125], v[246:249], 0
	ds_read_b128 v[122:125], v131 offset:1536
	s_waitcnt lgkmcnt(3)
	v_mfma_f32_16x16x32_bf16 v[4:7], v[126:129], v[242:245], v[4:7]
	v_mfma_f32_16x16x32_bf16 v[94:97], v[126:129], v[194:197], v[94:97]
	ds_read_b128 v[126:129], v133 offset:1536
	s_waitcnt lgkmcnt(3)
	v_mfma_f32_16x16x32_bf16 v[8:11], v[76:79], v[238:241], 0
	v_mfma_f32_16x16x32_bf16 v[98:101], v[76:79], v[246:249], 0
	ds_read_b128 v[76:79], v131 offset:2048
	s_waitcnt lgkmcnt(3)
	v_mfma_f32_16x16x32_bf16 v[8:11], v[80:83], v[242:245], v[8:11]
	v_mfma_f32_16x16x32_bf16 v[98:101], v[80:83], v[194:197], v[98:101]
	ds_read_b128 v[80:83], v133 offset:2048
	s_waitcnt lgkmcnt(3)
	v_mfma_f32_16x16x32_bf16 v[12:15], v[122:125], v[238:241], 0
	v_mfma_f32_16x16x32_bf16 v[102:105], v[122:125], v[246:249], 0
	ds_read_b128 v[122:125], v131 offset:2560
	s_waitcnt lgkmcnt(3)
	v_mfma_f32_16x16x32_bf16 v[12:15], v[126:129], v[242:245], v[12:15]
	v_mfma_f32_16x16x32_bf16 v[102:105], v[126:129], v[194:197], v[102:105]
	ds_read_b128 v[126:129], v133 offset:2560
	s_waitcnt lgkmcnt(3)
	v_mfma_f32_16x16x32_bf16 v[16:19], v[76:79], v[238:241], 0
	v_mfma_f32_16x16x32_bf16 v[106:109], v[76:79], v[246:249], 0
	ds_read_b128 v[76:79], v131 offset:3072
	s_waitcnt lgkmcnt(3)
	v_mfma_f32_16x16x32_bf16 v[16:19], v[80:83], v[242:245], v[16:19]
	v_mfma_f32_16x16x32_bf16 v[106:109], v[80:83], v[194:197], v[106:109]
	ds_read_b128 v[80:83], v133 offset:3072
	s_waitcnt lgkmcnt(3)
	v_mfma_f32_16x16x32_bf16 v[20:23], v[122:125], v[238:241], 0
	v_mfma_f32_16x16x32_bf16 v[110:113], v[122:125], v[246:249], 0
	ds_read_b128 v[122:125], v131 offset:3584
	s_waitcnt lgkmcnt(3)
	v_mfma_f32_16x16x32_bf16 v[20:23], v[126:129], v[242:245], v[20:23]
	v_mfma_f32_16x16x32_bf16 v[110:113], v[126:129], v[194:197], v[110:113]
	ds_read_b128 v[126:129], v133 offset:3584
	s_waitcnt lgkmcnt(3)
	v_mfma_f32_16x16x32_bf16 v[24:27], v[76:79], v[238:241], 0
	v_mfma_f32_16x16x32_bf16 v[114:117], v[76:79], v[246:249], 0
	s_waitcnt lgkmcnt(2)
	v_mfma_f32_16x16x32_bf16 v[24:27], v[80:83], v[242:245], v[24:27]
	v_mfma_f32_16x16x32_bf16 v[114:117], v[80:83], v[194:197], v[114:117]
	s_waitcnt lgkmcnt(1)
	v_mfma_f32_16x16x32_bf16 v[28:31], v[122:125], v[238:241], 0
	v_mfma_f32_16x16x32_bf16 v[118:121], v[122:125], v[246:249], 0
	s_waitcnt lgkmcnt(0)
	v_mfma_f32_16x16x32_bf16 v[28:31], v[126:129], v[242:245], v[28:31]
	v_mfma_f32_16x16x32_bf16 v[118:121], v[126:129], v[194:197], v[118:121]
	s_lshl_b32 s0, s56, 8
	s_add_u32 s0, s0, 0x20000
	s_add_u32 s4, s20, s0
	s_addc_u32 s5, s21, 0
	global_load_dwordx4 v[238:241], v251, s[4:5]
	global_load_dwordx4 v[242:245], v251, s[4:5] offset:64
	s_add_u32 s4, s4, 0x2000
	s_addc_u32 s5, s5, 0
	global_load_dwordx4 v[246:249], v251, s[4:5]
	global_load_dwordx4 v[194:197], v251, s[4:5] offset:64
	s_nop 7
	s_nop 7
	v_add_f32_e32 v0, v0, v75
	v_add_f32_e32 v1, v1, v75
	v_add_f32_e32 v2, v2, v75
	v_add_f32_e32 v3, v3, v75
	v_add_f32_e32 v90, v90, v84
	v_add_f32_e32 v91, v91, v84
	v_add_f32_e32 v92, v92, v84
	v_add_f32_e32 v93, v93, v84
	v_exp_f32_e32 v0, v0
	v_exp_f32_e32 v1, v1
	v_exp_f32_e32 v2, v2
	v_exp_f32_e32 v3, v3
	v_exp_f32_e32 v90, v90
	v_exp_f32_e32 v91, v91
	v_exp_f32_e32 v92, v92
	v_exp_f32_e32 v93, v93
	v_add_f32_e32 v0, 1.0, v0
	v_add_f32_e32 v1, 1.0, v1
	v_add_f32_e32 v2, 1.0, v2
	v_add_f32_e32 v3, 1.0, v3
	v_add_f32_e32 v90, 1.0, v90
	v_add_f32_e32 v91, 1.0, v91
	v_add_f32_e32 v92, 1.0, v92
	v_add_f32_e32 v93, 1.0, v93
	v_rcp_f32_e32 v0, v0
	v_rcp_f32_e32 v1, v1
	v_rcp_f32_e32 v2, v2
	v_rcp_f32_e32 v3, v3
	v_rcp_f32_e32 v90, v90
	v_rcp_f32_e32 v91, v91
	v_rcp_f32_e32 v92, v92
	v_rcp_f32_e32 v93, v93
	v_mul_f32_e32 v0, v85, v0
	v_mul_f32_e32 v1, v85, v1
	v_mul_f32_e32 v2, v85, v2
	v_mul_f32_e32 v3, v85, v3
	v_mul_f32_e32 v90, v90, v162
	v_mul_f32_e32 v91, v91, v163
	v_mul_f32_e32 v92, v92, v164
	v_mul_f32_e32 v93, v93, v165
	v_exp_f32_e32 v0, v0
	v_exp_f32_e32 v1, v1
	v_exp_f32_e32 v2, v2
	v_exp_f32_e32 v3, v3
	s_nop 0
	v_fma_f32 v138, -v0, v0, 1.0 clamp
	v_fma_f32 v139, -v1, v1, 1.0 clamp
	v_fma_f32 v140, -v2, v2, 1.0 clamp
	v_fma_f32 v141, -v3, v3, 1.0 clamp
	v_sqrt_f32_e32 v138, v138
	v_sqrt_f32_e32 v139, v139
	v_sqrt_f32_e32 v140, v140
	v_sqrt_f32_e32 v141, v141
	s_nop 0
	v_mul_f32_e32 v90, v138, v90
	v_mul_f32_e32 v91, v139, v91
	v_mul_f32_e32 v92, v140, v92
	v_mul_f32_e32 v93, v141, v93
	v_add_f32_e32 v4, v4, v75
	v_add_f32_e32 v5, v5, v75
	v_add_f32_e32 v6, v6, v75
	v_add_f32_e32 v7, v7, v75
	v_add_f32_e32 v94, v94, v84
	v_add_f32_e32 v95, v95, v84
	v_add_f32_e32 v96, v96, v84
	v_add_f32_e32 v97, v97, v84
	v_exp_f32_e32 v4, v4
	v_exp_f32_e32 v5, v5
	v_exp_f32_e32 v6, v6
	v_exp_f32_e32 v7, v7
	v_exp_f32_e32 v94, v94
	v_exp_f32_e32 v95, v95
	v_exp_f32_e32 v96, v96
	v_exp_f32_e32 v97, v97
	v_add_f32_e32 v4, 1.0, v4
	v_add_f32_e32 v5, 1.0, v5
	v_add_f32_e32 v6, 1.0, v6
	v_add_f32_e32 v7, 1.0, v7
	v_add_f32_e32 v94, 1.0, v94
	v_add_f32_e32 v95, 1.0, v95
	v_add_f32_e32 v96, 1.0, v96
	v_add_f32_e32 v97, 1.0, v97
; __device__ __forceinline__ float bf2f(u16 h) { return __uint_as_float(((unsigned)h) << 16); }
; __device__ __forceinline__ void lru_tile(const Params& P, int chunk, int head, int pass, char* smem_raw) {
;     ...
; #pragma unroll
;       for (int tc = 0; tc < 4; ++tc)
; #pragma unroll
;         for (int reg = 0; reg < 4; ++reg) {
;           const int tl = wid * 16 + (lane >> 4) * 4 + reg;
;           const int c = 16 * tc + (lane & 15);
;           const float r = __builtin_amdgcn_rcpf(1.f + __builtin_amdgcn_exp2f(acc[tc][reg] + ba[tc]));
;           const float ii = __builtin_amdgcn_rcpf(1.f + __builtin_amdgcn_exp2f(acc[tc + 4][reg] + bi[tc]));
;           const float la = -c8[tc] * r;
;           const float a = __builtin_amdgcn_exp2f(la);
;           const float ucv = bf2f(sm_uc[(sb * 64 + tl) * LDSS + c]);
;           const float bt = __builtin_amdgcn_sqrtf(fmaxf(1.f - a * a, 0.f)) * (ii * ucv);
;           sm_a[tl * 64 + c] = a;
;           sm_b[tl * 64 + c] = bt;
;         }
	v_rcp_f32_e32 v4, v4
	v_rcp_f32_e32 v5, v5
	v_rcp_f32_e32 v6, v6
	v_rcp_f32_e32 v7, v7
	v_rcp_f32_e32 v94, v94
	v_rcp_f32_e32 v95, v95
	v_rcp_f32_e32 v96, v96
	v_rcp_f32_e32 v97, v97
	v_mul_f32_e32 v4, v85, v4
	v_mul_f32_e32 v5, v85, v5
	v_mul_f32_e32 v6, v85, v6
	v_mul_f32_e32 v7, v85, v7
	v_mul_f32_e32 v94, v94, v166
	v_mul_f32_e32 v95, v95, v167
	v_mul_f32_e32 v96, v96, v168
	v_mul_f32_e32 v97, v97, v169
	v_exp_f32_e32 v4, v4
	v_exp_f32_e32 v5, v5
	v_exp_f32_e32 v6, v6
	v_exp_f32_e32 v7, v7
	s_nop 0
	v_fma_f32 v138, -v4, v4, 1.0 clamp
	v_fma_f32 v139, -v5, v5, 1.0 clamp
	v_fma_f32 v140, -v6, v6, 1.0 clamp
	v_fma_f32 v141, -v7, v7, 1.0 clamp
	v_sqrt_f32_e32 v138, v138
	v_sqrt_f32_e32 v139, v139
	v_sqrt_f32_e32 v140, v140
	v_sqrt_f32_e32 v141, v141
	s_nop 0
	v_mul_f32_e32 v94, v138, v94
	v_mul_f32_e32 v95, v139, v95
	v_mul_f32_e32 v96, v140, v96
	v_mul_f32_e32 v97, v141, v97
	v_add_f32_e32 v8, v8, v75
	v_add_f32_e32 v9, v9, v75
	v_add_f32_e32 v10, v10, v75
	v_add_f32_e32 v11, v11, v75
	v_add_f32_e32 v98, v98, v84
	v_add_f32_e32 v99, v99, v84
	v_add_f32_e32 v100, v100, v84
	v_add_f32_e32 v101, v101, v84
	v_exp_f32_e32 v8, v8
	v_exp_f32_e32 v9, v9
	v_exp_f32_e32 v10, v10
	v_exp_f32_e32 v11, v11
	v_exp_f32_e32 v98, v98
	v_exp_f32_e32 v99, v99
	v_exp_f32_e32 v100, v100
	v_exp_f32_e32 v101, v101
	v_add_f32_e32 v8, 1.0, v8
	v_add_f32_e32 v9, 1.0, v9
	v_add_f32_e32 v10, 1.0, v10
	v_add_f32_e32 v11, 1.0, v11
	v_add_f32_e32 v98, 1.0, v98
	v_add_f32_e32 v99, 1.0, v99
	v_add_f32_e32 v100, 1.0, v100
	v_add_f32_e32 v101, 1.0, v101
	v_rcp_f32_e32 v8, v8
	v_rcp_f32_e32 v9, v9
	v_rcp_f32_e32 v10, v10
	v_rcp_f32_e32 v11, v11
	v_rcp_f32_e32 v98, v98
	v_rcp_f32_e32 v99, v99
	v_rcp_f32_e32 v100, v100
	v_rcp_f32_e32 v101, v101
	v_mul_f32_e32 v8, v85, v8
	v_mul_f32_e32 v9, v85, v9
	v_mul_f32_e32 v10, v85, v10
	v_mul_f32_e32 v11, v85, v11
	v_mul_f32_e32 v98, v98, v170
	v_mul_f32_e32 v99, v99, v171
	v_mul_f32_e32 v100, v100, v172
	v_mul_f32_e32 v101, v101, v173
	v_exp_f32_e32 v8, v8
	v_exp_f32_e32 v9, v9
	v_exp_f32_e32 v10, v10
	v_exp_f32_e32 v11, v11
	s_nop 0
	v_fma_f32 v138, -v8, v8, 1.0 clamp
	v_fma_f32 v139, -v9, v9, 1.0 clamp
	v_fma_f32 v140, -v10, v10, 1.0 clamp
	v_fma_f32 v141, -v11, v11, 1.0 clamp
	v_sqrt_f32_e32 v138, v138
	v_sqrt_f32_e32 v139, v139
	v_sqrt_f32_e32 v140, v140
	v_sqrt_f32_e32 v141, v141
	s_nop 0
	v_mul_f32_e32 v98, v138, v98
	v_mul_f32_e32 v99, v139, v99
	v_mul_f32_e32 v100, v140, v100
	v_mul_f32_e32 v101, v141, v101
	v_add_f32_e32 v12, v12, v75
	v_add_f32_e32 v13, v13, v75
	v_add_f32_e32 v14, v14, v75
	v_add_f32_e32 v15, v15, v75
	v_add_f32_e32 v102, v102, v84
	v_add_f32_e32 v103, v103, v84
	v_add_f32_e32 v104, v104, v84
	v_add_f32_e32 v105, v105, v84
	v_exp_f32_e32 v12, v12
	v_exp_f32_e32 v13, v13
	v_exp_f32_e32 v14, v14
	v_exp_f32_e32 v15, v15
	v_exp_f32_e32 v102, v102
	v_exp_f32_e32 v103, v103
	v_exp_f32_e32 v104, v104
	v_exp_f32_e32 v105, v105
	v_add_f32_e32 v12, 1.0, v12
	v_add_f32_e32 v13, 1.0, v13
	v_add_f32_e32 v14, 1.0, v14
	v_add_f32_e32 v15, 1.0, v15
	v_add_f32_e32 v102, 1.0, v102
	v_add_f32_e32 v103, 1.0, v103
	v_add_f32_e32 v104, 1.0, v104
	v_add_f32_e32 v105, 1.0, v105
	v_rcp_f32_e32 v12, v12
	v_rcp_f32_e32 v13, v13
	v_rcp_f32_e32 v14, v14
	v_rcp_f32_e32 v15, v15
	v_rcp_f32_e32 v102, v102
	v_rcp_f32_e32 v103, v103
	v_rcp_f32_e32 v104, v104
	v_rcp_f32_e32 v105, v105
	v_mul_f32_e32 v12, v85, v12
	v_mul_f32_e32 v13, v85, v13
	v_mul_f32_e32 v14, v85, v14
	v_mul_f32_e32 v15, v85, v15
	v_mul_f32_e32 v102, v102, v174
	v_mul_f32_e32 v103, v103, v175
	v_mul_f32_e32 v104, v104, v176
	v_mul_f32_e32 v105, v105, v177
	v_exp_f32_e32 v12, v12
	v_exp_f32_e32 v13, v13
	v_exp_f32_e32 v14, v14
	v_exp_f32_e32 v15, v15
	s_nop 0
	v_fma_f32 v138, -v12, v12, 1.0 clamp
	v_fma_f32 v139, -v13, v13, 1.0 clamp
	v_fma_f32 v140, -v14, v14, 1.0 clamp
	v_fma_f32 v141, -v15, v15, 1.0 clamp
	v_sqrt_f32_e32 v138, v138
	v_sqrt_f32_e32 v139, v139
	v_sqrt_f32_e32 v140, v140
	v_sqrt_f32_e32 v141, v141
	s_nop 0
	v_mul_f32_e32 v102, v138, v102
	v_mul_f32_e32 v103, v139, v103
	v_mul_f32_e32 v104, v140, v104
	v_mul_f32_e32 v105, v141, v105
	v_add_f32_e32 v16, v16, v75
	v_add_f32_e32 v17, v17, v75
	v_add_f32_e32 v18, v18, v75
	v_add_f32_e32 v19, v19, v75
	v_add_f32_e32 v106, v106, v84
	v_add_f32_e32 v107, v107, v84
	v_add_f32_e32 v108, v108, v84
	v_add_f32_e32 v109, v109, v84
	v_exp_f32_e32 v16, v16
	v_exp_f32_e32 v17, v17
	v_exp_f32_e32 v18, v18
	v_exp_f32_e32 v19, v19
	v_exp_f32_e32 v106, v106
	v_exp_f32_e32 v107, v107
	v_exp_f32_e32 v108, v108
	v_exp_f32_e32 v109, v109
	v_add_f32_e32 v16, 1.0, v16
	v_add_f32_e32 v17, 1.0, v17
	v_add_f32_e32 v18, 1.0, v18
	v_add_f32_e32 v19, 1.0, v19
	v_add_f32_e32 v106, 1.0, v106
	v_add_f32_e32 v107, 1.0, v107
	v_add_f32_e32 v108, 1.0, v108
	v_add_f32_e32 v109, 1.0, v109
	v_rcp_f32_e32 v16, v16
	v_rcp_f32_e32 v17, v17
	v_rcp_f32_e32 v18, v18
	v_rcp_f32_e32 v19, v19
	v_rcp_f32_e32 v106, v106
	v_rcp_f32_e32 v107, v107
	v_rcp_f32_e32 v108, v108
	v_rcp_f32_e32 v109, v109
	v_mul_f32_e32 v16, v85, v16
	v_mul_f32_e32 v17, v85, v17
	v_mul_f32_e32 v18, v85, v18
	v_mul_f32_e32 v19, v85, v19
	v_mul_f32_e32 v106, v106, v178
	v_mul_f32_e32 v107, v107, v179
	v_mul_f32_e32 v108, v108, v180
	v_mul_f32_e32 v109, v109, v181
	v_exp_f32_e32 v16, v16
	v_exp_f32_e32 v17, v17
	v_exp_f32_e32 v18, v18
	v_exp_f32_e32 v19, v19
	s_nop 0
	v_fma_f32 v138, -v16, v16, 1.0 clamp
	v_fma_f32 v139, -v17, v17, 1.0 clamp
	v_fma_f32 v140, -v18, v18, 1.0 clamp
	v_fma_f32 v141, -v19, v19, 1.0 clamp
	v_sqrt_f32_e32 v138, v138
	v_sqrt_f32_e32 v139, v139
	v_sqrt_f32_e32 v140, v140
	v_sqrt_f32_e32 v141, v141
	s_nop 0
	v_mul_f32_e32 v106, v138, v106
	v_mul_f32_e32 v107, v139, v107
; __device__ __forceinline__ float bf2f(u16 h) { return __uint_as_float(((unsigned)h) << 16); }
; __device__ __forceinline__ void lru_tile(const Params& P, int chunk, int head, int pass, char* smem_raw) {
;     ...
; #pragma unroll
;       for (int tc = 0; tc < 4; ++tc)
; #pragma unroll
;         for (int reg = 0; reg < 4; ++reg) {
;           const int tl = wid * 16 + (lane >> 4) * 4 + reg;
;           const int c = 16 * tc + (lane & 15);
;           const float r = __builtin_amdgcn_rcpf(1.f + __builtin_amdgcn_exp2f(acc[tc][reg] + ba[tc]));
;           const float ii = __builtin_amdgcn_rcpf(1.f + __builtin_amdgcn_exp2f(acc[tc + 4][reg] + bi[tc]));
;           const float la = -c8[tc] * r;
;           const float a = __builtin_amdgcn_exp2f(la);
;           const float ucv = bf2f(sm_uc[(sb * 64 + tl) * LDSS + c]);
;           const float bt = __builtin_amdgcn_sqrtf(fmaxf(1.f - a * a, 0.f)) * (ii * ucv);
;           sm_a[tl * 64 + c] = a;
;           sm_b[tl * 64 + c] = bt;
;         }
;       __syncthreads();
;       const int pos = (d == 0) ? q : 3 - q;
;       {
;         float Pp = 1.f, H = 0.f;
; #pragma unroll 4
;         for (int i = 0; i < 16; ++i) {
;           const int tl = (d == 0) ? (q * 16 + i) : (q * 16 + 15 - i);
;           const float a = sm_a[tl * 64 + ch], b = sm_b[tl * 64 + ch];
;           H = a * H + b; Pp *= a;
;         }
	v_mul_f32_e32 v108, v140, v108
	v_mul_f32_e32 v109, v141, v109
	v_add_f32_e32 v20, v20, v75
	v_add_f32_e32 v21, v21, v75
	v_add_f32_e32 v22, v22, v75
	v_add_f32_e32 v23, v23, v75
	v_add_f32_e32 v110, v110, v84
	v_add_f32_e32 v111, v111, v84
	v_add_f32_e32 v112, v112, v84
	v_add_f32_e32 v113, v113, v84
	v_exp_f32_e32 v20, v20
	v_exp_f32_e32 v21, v21
	v_exp_f32_e32 v22, v22
	v_exp_f32_e32 v23, v23
	v_exp_f32_e32 v110, v110
	v_exp_f32_e32 v111, v111
	v_exp_f32_e32 v112, v112
	v_exp_f32_e32 v113, v113
	v_add_f32_e32 v20, 1.0, v20
	v_add_f32_e32 v21, 1.0, v21
	v_add_f32_e32 v22, 1.0, v22
	v_add_f32_e32 v23, 1.0, v23
	v_add_f32_e32 v110, 1.0, v110
	v_add_f32_e32 v111, 1.0, v111
	v_add_f32_e32 v112, 1.0, v112
	v_add_f32_e32 v113, 1.0, v113
	v_rcp_f32_e32 v20, v20
	v_rcp_f32_e32 v21, v21
	v_rcp_f32_e32 v22, v22
	v_rcp_f32_e32 v23, v23
	v_rcp_f32_e32 v110, v110
	v_rcp_f32_e32 v111, v111
	v_rcp_f32_e32 v112, v112
	v_rcp_f32_e32 v113, v113
	v_mul_f32_e32 v20, v85, v20
	v_mul_f32_e32 v21, v85, v21
	v_mul_f32_e32 v22, v85, v22
	v_mul_f32_e32 v23, v85, v23
	v_mul_f32_e32 v110, v110, v182
	v_mul_f32_e32 v111, v111, v183
	v_mul_f32_e32 v112, v112, v184
	v_mul_f32_e32 v113, v113, v185
	v_exp_f32_e32 v20, v20
	v_exp_f32_e32 v21, v21
	v_exp_f32_e32 v22, v22
	v_exp_f32_e32 v23, v23
	s_nop 0
	v_fma_f32 v138, -v20, v20, 1.0 clamp
	v_fma_f32 v139, -v21, v21, 1.0 clamp
	v_fma_f32 v140, -v22, v22, 1.0 clamp
	v_fma_f32 v141, -v23, v23, 1.0 clamp
	v_sqrt_f32_e32 v138, v138
	v_sqrt_f32_e32 v139, v139
	v_sqrt_f32_e32 v140, v140
	v_sqrt_f32_e32 v141, v141
	s_nop 0
	v_mul_f32_e32 v110, v138, v110
	v_mul_f32_e32 v111, v139, v111
	v_mul_f32_e32 v112, v140, v112
	v_mul_f32_e32 v113, v141, v113
	v_add_f32_e32 v24, v24, v75
	v_add_f32_e32 v25, v25, v75
	v_add_f32_e32 v26, v26, v75
	v_add_f32_e32 v27, v27, v75
	v_add_f32_e32 v114, v114, v84
	v_add_f32_e32 v115, v115, v84
	v_add_f32_e32 v116, v116, v84
	v_add_f32_e32 v117, v117, v84
	v_exp_f32_e32 v24, v24
	v_exp_f32_e32 v25, v25
	v_exp_f32_e32 v26, v26
	v_exp_f32_e32 v27, v27
	v_exp_f32_e32 v114, v114
	v_exp_f32_e32 v115, v115
	v_exp_f32_e32 v116, v116
	v_exp_f32_e32 v117, v117
	v_add_f32_e32 v24, 1.0, v24
	v_add_f32_e32 v25, 1.0, v25
	v_add_f32_e32 v26, 1.0, v26
	v_add_f32_e32 v27, 1.0, v27
	v_add_f32_e32 v114, 1.0, v114
	v_add_f32_e32 v115, 1.0, v115
	v_add_f32_e32 v116, 1.0, v116
	v_add_f32_e32 v117, 1.0, v117
	v_rcp_f32_e32 v24, v24
	v_rcp_f32_e32 v25, v25
	v_rcp_f32_e32 v26, v26
	v_rcp_f32_e32 v27, v27
	v_rcp_f32_e32 v114, v114
	v_rcp_f32_e32 v115, v115
	v_rcp_f32_e32 v116, v116
	v_rcp_f32_e32 v117, v117
	v_mul_f32_e32 v24, v85, v24
	v_mul_f32_e32 v25, v85, v25
	v_mul_f32_e32 v26, v85, v26
	v_mul_f32_e32 v27, v85, v27
	v_mul_f32_e32 v114, v114, v186
	v_mul_f32_e32 v115, v115, v187
	v_mul_f32_e32 v116, v116, v188
	v_mul_f32_e32 v117, v117, v189
	v_exp_f32_e32 v24, v24
	v_exp_f32_e32 v25, v25
	v_exp_f32_e32 v26, v26
	v_exp_f32_e32 v27, v27
	s_nop 0
	v_fma_f32 v138, -v24, v24, 1.0 clamp
	v_fma_f32 v139, -v25, v25, 1.0 clamp
	v_fma_f32 v140, -v26, v26, 1.0 clamp
	v_fma_f32 v141, -v27, v27, 1.0 clamp
	v_sqrt_f32_e32 v138, v138
	v_sqrt_f32_e32 v139, v139
	v_sqrt_f32_e32 v140, v140
	v_sqrt_f32_e32 v141, v141
	s_nop 0
	v_mul_f32_e32 v114, v138, v114
	v_mul_f32_e32 v115, v139, v115
	v_mul_f32_e32 v116, v140, v116
	v_mul_f32_e32 v117, v141, v117
	v_add_f32_e32 v28, v28, v75
	v_add_f32_e32 v29, v29, v75
	v_add_f32_e32 v30, v30, v75
	v_add_f32_e32 v31, v31, v75
	v_add_f32_e32 v118, v118, v84
	v_add_f32_e32 v119, v119, v84
	v_add_f32_e32 v120, v120, v84
	v_add_f32_e32 v121, v121, v84
	v_exp_f32_e32 v28, v28
	v_exp_f32_e32 v29, v29
	v_exp_f32_e32 v30, v30
	v_exp_f32_e32 v31, v31
	v_exp_f32_e32 v118, v118
	v_exp_f32_e32 v119, v119
	v_exp_f32_e32 v120, v120
	v_exp_f32_e32 v121, v121
	v_add_f32_e32 v28, 1.0, v28
	v_add_f32_e32 v29, 1.0, v29
	v_add_f32_e32 v30, 1.0, v30
	v_add_f32_e32 v31, 1.0, v31
	v_add_f32_e32 v118, 1.0, v118
	v_add_f32_e32 v119, 1.0, v119
	v_add_f32_e32 v120, 1.0, v120
	v_add_f32_e32 v121, 1.0, v121
	v_rcp_f32_e32 v28, v28
	v_rcp_f32_e32 v29, v29
	v_rcp_f32_e32 v30, v30
	v_rcp_f32_e32 v31, v31
	v_rcp_f32_e32 v118, v118
	v_rcp_f32_e32 v119, v119
	v_rcp_f32_e32 v120, v120
	v_rcp_f32_e32 v121, v121
	v_mul_f32_e32 v28, v85, v28
	v_mul_f32_e32 v29, v85, v29
	v_mul_f32_e32 v30, v85, v30
	v_mul_f32_e32 v31, v85, v31
	v_mul_f32_e32 v118, v118, v190
	v_mul_f32_e32 v119, v119, v191
	v_mul_f32_e32 v120, v120, v192
	v_mul_f32_e32 v121, v121, v193
	v_exp_f32_e32 v28, v28
	v_exp_f32_e32 v29, v29
	v_exp_f32_e32 v30, v30
	v_exp_f32_e32 v31, v31
	s_nop 0
	v_fma_f32 v138, -v28, v28, 1.0 clamp
	v_fma_f32 v139, -v29, v29, 1.0 clamp
	v_fma_f32 v140, -v30, v30, 1.0 clamp
	v_fma_f32 v141, -v31, v31, 1.0 clamp
	v_sqrt_f32_e32 v138, v138
	v_sqrt_f32_e32 v139, v139
	v_sqrt_f32_e32 v140, v140
	v_sqrt_f32_e32 v141, v141
	s_nop 0
	v_mul_f32_e32 v118, v138, v118
	v_mul_f32_e32 v119, v139, v119
	v_mul_f32_e32 v120, v140, v120
	v_mul_f32_e32 v121, v141, v121
	v_mov_b32_e32 v253, v0
	v_mov_b32_e32 v254, v90
	v_fma_f32 v254, v1, v254, v91
	v_mul_f32_e32 v253, v253, v1
	v_fma_f32 v254, v2, v254, v92
	v_mul_f32_e32 v253, v253, v2
	v_fma_f32 v254, v3, v254, v93
	v_mul_f32_e32 v253, v253, v3
	v_fma_f32 v254, v4, v254, v94
	v_mul_f32_e32 v253, v253, v4
	v_fma_f32 v254, v5, v254, v95
	v_mul_f32_e32 v253, v253, v5
	v_fma_f32 v254, v6, v254, v96
	v_mul_f32_e32 v253, v253, v6
	v_fma_f32 v254, v7, v254, v97
	v_mul_f32_e32 v253, v253, v7
	v_fma_f32 v254, v8, v254, v98
	v_mul_f32_e32 v253, v253, v8
	v_fma_f32 v254, v9, v254, v99
	v_mul_f32_e32 v253, v253, v9
	v_fma_f32 v254, v10, v254, v100
	v_mul_f32_e32 v253, v253, v10
	v_fma_f32 v254, v11, v254, v101
; __device__ __forceinline__ void lru_tile(const Params& P, int chunk, int head, int pass, char* smem_raw) {
;     ...
;         const bf16x8 af = *reinterpret_cast<const bf16x8*>(&sm_uc[(sb * 64 + wid * 16 + (lane & 15)) * LDSS + s * 32 + (lane >> 4) * 8]);
; #pragma unroll
;         for (int t = 0; t < 8; ++t) {
;     ...
;         float Pp = 1.f, H = 0.f;
; #pragma unroll 4
;         for (int i = 0; i < 16; ++i) {
;           const int tl = (d == 0) ? (q * 16 + i) : (q * 16 + 15 - i);
;           const float a = sm_a[tl * 64 + ch], b = sm_b[tl * 64 + ch];
;           H = a * H + b; Pp *= a;
;         }
;         sm_ph[pos * 64 + ch] = make_float2(Pp, H);
;       }
;       __syncthreads();
;       const float2 p0 = sm_ph[ch], p1 = sm_ph[64 + ch], p2 = sm_ph[128 + ch], p3 = sm_ph[192 + ch];
;       if (pass == 2) {
;         float hin = cB;
;         if (pos > 0) hin = p0.x * hin + p0.y;
;         if (pos > 1) hin = p1.x * hin + p1.y;
;         if (pos > 2) hin = p2.x * hin + p2.y;
;         float h = hin;
;         float hfp[16], gp[16];
;         if (d == 1) {
; #pragma unroll
;           for (int i = 0; i < 16; ++i) {
;             const long rowp = row0 + sb * 64 + q * 16 + 15 - i;
;             hfp[i] = hfbuf[rowp * 512 + gch];
;             gp[i] = bf2f(P.zq[rowp * 1536 + 512 + gch]);
;           }
;         }
; #pragma unroll
;         for (int i = 0; i < 16; ++i) {
;           const int tl = (d == 0) ? (q * 16 + i) : (q * 16 + 15 - i);
;           const float a = sm_a[tl * 64 + ch], b = sm_b[tl * 64 + ch];
;           h = a * h + b;
;           const long row = row0 + sb * 64 + tl;
;           if (d == 0) {
;             hfw[row * 512 + gch] = h;
;           } else {
;             const float hfv = hfp[i];
;             const float g = gp[i];
;             const float tz = 0.7978845608028654f * (g + 0.044715f * g * g * g);
;             const float th = 1.f - 2.f * __builtin_amdgcn_rcpf(1.f + __expf(2.f * tz));
;             const float ge = 0.5f * g * (1.f + th);
;             P.cat[row * 1024 + gch] = f2bf((hfv + h) * ge);
;           }
;         }
;       }
;       cB = p0.x * cB + p0.y; cA *= p0.x;
;       cB = p1.x * cB + p1.y; cA *= p1.x;
;       cB = p2.x * cB + p2.y; cA *= p2.x;
;       cB = p3.x * cB + p3.y; cA *= p3.x;
;       __syncthreads();
;     }
;     if (pass == 1 && q == 0) P.summ[((long)d * 264 + chunk) * 512 + gch] = make_float2(cA, cB);
	v_mul_f32_e32 v253, v253, v11
	v_fma_f32 v254, v12, v254, v102
	v_mul_f32_e32 v253, v253, v12
	v_fma_f32 v254, v13, v254, v103
	v_mul_f32_e32 v253, v253, v13
	v_fma_f32 v254, v14, v254, v104
	v_mul_f32_e32 v253, v253, v14
	v_fma_f32 v254, v15, v254, v105
	v_mul_f32_e32 v253, v253, v15
	v_fma_f32 v254, v16, v254, v106
	v_mul_f32_e32 v253, v253, v16
	v_fma_f32 v254, v17, v254, v107
	v_mul_f32_e32 v253, v253, v17
	v_fma_f32 v254, v18, v254, v108
	v_mul_f32_e32 v253, v253, v18
	v_fma_f32 v254, v19, v254, v109
	v_mul_f32_e32 v253, v253, v19
	v_fma_f32 v254, v20, v254, v110
	v_mul_f32_e32 v253, v253, v20
	v_fma_f32 v254, v21, v254, v111
	v_mul_f32_e32 v253, v253, v21
	v_fma_f32 v254, v22, v254, v112
	v_mul_f32_e32 v253, v253, v22
	v_fma_f32 v254, v23, v254, v113
	v_mul_f32_e32 v253, v253, v23
	v_fma_f32 v254, v24, v254, v114
	v_mul_f32_e32 v253, v253, v24
	v_fma_f32 v254, v25, v254, v115
	v_mul_f32_e32 v253, v253, v25
	v_fma_f32 v254, v26, v254, v116
	v_mul_f32_e32 v253, v253, v26
	v_fma_f32 v254, v27, v254, v117
	v_mul_f32_e32 v253, v253, v27
	v_fma_f32 v254, v28, v254, v118
	v_mul_f32_e32 v253, v253, v28
	v_fma_f32 v254, v29, v254, v119
	v_mul_f32_e32 v253, v253, v29
	v_fma_f32 v254, v30, v254, v120
	v_mul_f32_e32 v253, v253, v30
	v_fma_f32 v254, v31, v254, v121
	v_mul_f32_e32 v253, v253, v31
	v_mov_b32_e32 v138, v253
	v_mov_b32_e32 v139, v253
	s_nop 1
	v_permlane16_swap_b32_e32 v138, v139
	v_mov_b32_e32 v140, v138
	v_mov_b32_e32 v141, v139
	s_nop 1
	v_permlane32_swap_b32_e32 v138, v140
	v_permlane32_swap_b32_e32 v139, v141
	v_mov_b32_e32 v198, v254
	v_mov_b32_e32 v199, v254
	s_nop 1
	v_permlane16_swap_b32_e32 v198, v199
	v_mov_b32_e32 v200, v198
	v_mov_b32_e32 v201, v199
	s_nop 1
	v_permlane32_swap_b32_e32 v198, v200
	v_permlane32_swap_b32_e32 v199, v201
	v_mov_b32_e32 v136, 0
	v_fma_f32 v150, v138, v136, v198
	v_fma_f32 v151, v139, v150, v199
	v_fma_f32 v202, v140, v151, v200
	v_fma_f32 v254, v141, v202, v201
	v_mul_f32_e32 v253, v138, v139
	v_mul_f32_e32 v253, v253, v140
	v_mul_f32_e32 v200, v253, v141
	v_mov_b32_e32 v201, v254
	s_add_u32 s0, s71, 0
	s_lshl_b32 s0, s0, 12
	s_lshl_b32 s1, s56, 3
	s_add_u32 s0, s0, s1
	s_add_u32 s4, s18, s0
	s_addc_u32 s5, s19, 0
	global_store_dwordx2 v250, v[200:201], s[4:5]
	ds_read_b128 v[76:79], v131 offset:0
	ds_read_b128 v[80:83], v133 offset:0
	ds_read_b128 v[122:125], v131 offset:512
	ds_read_b128 v[126:129], v133 offset:512
	s_waitcnt vmcnt(1)
	s_waitcnt lgkmcnt(3)
	v_mfma_f32_16x16x32_bf16 v[0:3], v[76:79], v[238:241], 0
	v_mfma_f32_16x16x32_bf16 v[90:93], v[76:79], v[246:249], 0
	ds_read_b128 v[76:79], v131 offset:1024
	s_waitcnt lgkmcnt(3)
	v_mfma_f32_16x16x32_bf16 v[0:3], v[80:83], v[242:245], v[0:3]
	v_mfma_f32_16x16x32_bf16 v[90:93], v[80:83], v[194:197], v[90:93]
	ds_read_b128 v[80:83], v133 offset:1024
	s_waitcnt lgkmcnt(3)
	v_mfma_f32_16x16x32_bf16 v[4:7], v[122:125], v[238:241], 0
	v_mfma_f32_16x16x32_bf16 v[94:97], v[122:125], v[246:249], 0
	ds_read_b128 v[122:125], v131 offset:1536
	s_waitcnt lgkmcnt(3)
	v_mfma_f32_16x16x32_bf16 v[4:7], v[126:129], v[242:245], v[4:7]
	v_mfma_f32_16x16x32_bf16 v[94:97], v[126:129], v[194:197], v[94:97]
	ds_read_b128 v[126:129], v133 offset:1536
	s_waitcnt lgkmcnt(3)
	v_mfma_f32_16x16x32_bf16 v[8:11], v[76:79], v[238:241], 0
	v_mfma_f32_16x16x32_bf16 v[98:101], v[76:79], v[246:249], 0
	ds_read_b128 v[76:79], v131 offset:2048
	s_waitcnt lgkmcnt(3)
	v_mfma_f32_16x16x32_bf16 v[8:11], v[80:83], v[242:245], v[8:11]
	v_mfma_f32_16x16x32_bf16 v[98:101], v[80:83], v[194:197], v[98:101]
	ds_read_b128 v[80:83], v133 offset:2048
	s_waitcnt lgkmcnt(3)
	v_mfma_f32_16x16x32_bf16 v[12:15], v[122:125], v[238:241], 0
	v_mfma_f32_16x16x32_bf16 v[102:105], v[122:125], v[246:249], 0
	ds_read_b128 v[122:125], v131 offset:2560
	s_waitcnt lgkmcnt(3)
	v_mfma_f32_16x16x32_bf16 v[12:15], v[126:129], v[242:245], v[12:15]
	v_mfma_f32_16x16x32_bf16 v[102:105], v[126:129], v[194:197], v[102:105]
	ds_read_b128 v[126:129], v133 offset:2560
	s_waitcnt lgkmcnt(3)
	v_mfma_f32_16x16x32_bf16 v[16:19], v[76:79], v[238:241], 0
	v_mfma_f32_16x16x32_bf16 v[106:109], v[76:79], v[246:249], 0
	ds_read_b128 v[76:79], v131 offset:3072
	s_waitcnt lgkmcnt(3)
	v_mfma_f32_16x16x32_bf16 v[16:19], v[80:83], v[242:245], v[16:19]
	v_mfma_f32_16x16x32_bf16 v[106:109], v[80:83], v[194:197], v[106:109]
	ds_read_b128 v[80:83], v133 offset:3072
	s_waitcnt lgkmcnt(3)
	v_mfma_f32_16x16x32_bf16 v[20:23], v[122:125], v[238:241], 0
	v_mfma_f32_16x16x32_bf16 v[110:113], v[122:125], v[246:249], 0
	ds_read_b128 v[122:125], v131 offset:3584
	s_waitcnt lgkmcnt(3)
	v_mfma_f32_16x16x32_bf16 v[20:23], v[126:129], v[242:245], v[20:23]
	v_mfma_f32_16x16x32_bf16 v[110:113], v[126:129], v[194:197], v[110:113]
	ds_read_b128 v[126:129], v133 offset:3584
	s_waitcnt lgkmcnt(3)
	v_mfma_f32_16x16x32_bf16 v[24:27], v[76:79], v[238:241], 0
	v_mfma_f32_16x16x32_bf16 v[114:117], v[76:79], v[246:249], 0
	s_waitcnt lgkmcnt(2)
	v_mfma_f32_16x16x32_bf16 v[24:27], v[80:83], v[242:245], v[24:27]
	v_mfma_f32_16x16x32_bf16 v[114:117], v[80:83], v[194:197], v[114:117]
	s_waitcnt lgkmcnt(1)
	v_mfma_f32_16x16x32_bf16 v[28:31], v[122:125], v[238:241], 0
	v_mfma_f32_16x16x32_bf16 v[118:121], v[122:125], v[246:249], 0
	s_waitcnt lgkmcnt(0)
; __device__ __forceinline__ void lru_tile(const Params& P, int chunk, int head, int pass, char* smem_raw) {
;     ...
;       *reinterpret_cast<uint4*>(&sm_w[rowi * LDSS + kg * 8]) = ldg16(P.wg + ((long)(d * 8 + head) * 128 + rowi) * 64 + kg * 8);
;     }
;     float ba[4], bi[4], c8[4];
; #pragma unroll
;     for (int tc = 0; tc < 4; ++tc) {
;       const int cidx = d * 512 + head * 64 + 16 * tc + (lane & 15);
;       ba[tc] = P.b_a[cidx] * -1.4426950408889634f; bi[tc] = P.b_i[cidx] * -1.4426950408889634f;
;       const float nl = -P.lam[cidx];
;       const float e_ = __expf(nl);
;       const float sp = (nl > 20.f) ? nl
;                      : (e_ < 0.03f ? e_ * (1.f - e_ * (0.5f - e_ * (0.33333334f - 0.25f * e_))) : __logf(1.f + e_));
;       c8[tc] = 8.f * 1.4426950408889634f * sp;
;     }
;     __syncthreads();
;     float cA = 1.f, cB = (pass == 2) ? sm_init[d * 64 + ch] : 0.f;
;     for (int sbi = 0; sbi < 2; ++sbi) {
;       const int sb = (d == 0) ? sbi : 1 - sbi;
;       f32x4 acc[8];
; #pragma unroll
;       for (int t = 0; t < 8; ++t) acc[t] = f32x4{0.f, 0.f, 0.f, 0.f};
; #pragma unroll
;       for (int s = 0; s < 2; ++s) {
;         const bf16x8 af = *reinterpret_cast<const bf16x8*>(&sm_uc[(sb * 64 + wid * 16 + (lane & 15)) * LDSS + s * 32 + (lane >> 4) * 8]);
; #pragma unroll
;         for (int t = 0; t < 8; ++t) {
;           const bf16x8 bfr = *reinterpret_cast<const bf16x8*>(&sm_w[(t * 16 + (lane & 15)) * LDSS + s * 32 + (lane >> 4) * 8]);
;           acc[t] = __builtin_amdgcn_mfma_f32_16x16x32_bf16(af, bfr, acc[t], 0, 0, 0);
;         }
;       }
; #pragma unroll
;       for (int tc = 0; tc < 4; ++tc)
; #pragma unroll
;         for (int reg = 0; reg < 4; ++reg) {
;           const int tl = wid * 16 + (lane >> 4) * 4 + reg;
;           const int c = 16 * tc + (lane & 15);
;           const float r = __builtin_amdgcn_rcpf(1.f + __builtin_amdgcn_exp2f(acc[tc][reg] + ba[tc]));
;           const float ii = __builtin_amdgcn_rcpf(1.f + __builtin_amdgcn_exp2f(acc[tc + 4][reg] + bi[tc]));
;           const float la = -c8[tc] * r;
;           const float a = __builtin_amdgcn_exp2f(la);
;           const float ucv = bf2f(sm_uc[(sb * 64 + tl) * LDSS + c]);
;           const float bt = __builtin_amdgcn_sqrtf(fmaxf(1.f - a * a, 0.f)) * (ii * ucv);
;           sm_a[tl * 64 + c] = a;
;           sm_b[tl * 64 + c] = bt;
;         }
	v_mfma_f32_16x16x32_bf16 v[28:31], v[126:129], v[242:245], v[28:31]
	v_mfma_f32_16x16x32_bf16 v[118:121], v[126:129], v[194:197], v[118:121]
	s_lshl_b32 s0, s56, 8
	s_add_u32 s0, s0, 0x0
	s_add_u32 s4, s20, s0
	s_addc_u32 s5, s21, 0
	global_load_dwordx4 v[238:241], v251, s[4:5]
	global_load_dwordx4 v[242:245], v251, s[4:5] offset:64
	s_add_u32 s4, s4, 0x2000
	s_addc_u32 s5, s5, 0
	global_load_dwordx4 v[246:249], v251, s[4:5]
	global_load_dwordx4 v[194:197], v251, s[4:5] offset:64
	s_nop 7
	s_nop 7
	v_add_f32_e32 v0, v0, v145
	v_add_f32_e32 v1, v1, v145
	v_add_f32_e32 v2, v2, v145
	v_add_f32_e32 v3, v3, v145
	v_add_f32_e32 v90, v90, v146
	v_add_f32_e32 v91, v91, v146
	v_add_f32_e32 v92, v92, v146
	v_add_f32_e32 v93, v93, v146
	v_exp_f32_e32 v0, v0
	v_exp_f32_e32 v1, v1
	v_exp_f32_e32 v2, v2
	v_exp_f32_e32 v3, v3
	v_exp_f32_e32 v90, v90
	v_exp_f32_e32 v91, v91
	v_exp_f32_e32 v92, v92
	v_exp_f32_e32 v93, v93
	v_add_f32_e32 v0, 1.0, v0
	v_add_f32_e32 v1, 1.0, v1
	v_add_f32_e32 v2, 1.0, v2
	v_add_f32_e32 v3, 1.0, v3
	v_add_f32_e32 v90, 1.0, v90
	v_add_f32_e32 v91, 1.0, v91
	v_add_f32_e32 v92, 1.0, v92
	v_add_f32_e32 v93, 1.0, v93
	v_rcp_f32_e32 v0, v0
	v_rcp_f32_e32 v1, v1
	v_rcp_f32_e32 v2, v2
	v_rcp_f32_e32 v3, v3
	v_rcp_f32_e32 v90, v90
	v_rcp_f32_e32 v91, v91
	v_rcp_f32_e32 v92, v92
	v_rcp_f32_e32 v93, v93
	v_mul_f32_e32 v0, v147, v0
	v_mul_f32_e32 v1, v147, v1
	v_mul_f32_e32 v2, v147, v2
	v_mul_f32_e32 v3, v147, v3
	v_mul_f32_e32 v90, v90, v162
	v_mul_f32_e32 v91, v91, v163
	v_mul_f32_e32 v92, v92, v164
	v_mul_f32_e32 v93, v93, v165
	v_exp_f32_e32 v0, v0
	v_exp_f32_e32 v1, v1
	v_exp_f32_e32 v2, v2
	v_exp_f32_e32 v3, v3
	s_nop 0
	v_fma_f32 v138, -v0, v0, 1.0 clamp
	v_fma_f32 v139, -v1, v1, 1.0 clamp
	v_fma_f32 v140, -v2, v2, 1.0 clamp
	v_fma_f32 v141, -v3, v3, 1.0 clamp
	v_sqrt_f32_e32 v138, v138
	v_sqrt_f32_e32 v139, v139
	v_sqrt_f32_e32 v140, v140
	v_sqrt_f32_e32 v141, v141
	s_nop 0
	v_mul_f32_e32 v90, v138, v90
	v_mul_f32_e32 v91, v139, v91
	v_mul_f32_e32 v92, v140, v92
	v_mul_f32_e32 v93, v141, v93
	v_add_f32_e32 v4, v4, v145
	v_add_f32_e32 v5, v5, v145
	v_add_f32_e32 v6, v6, v145
	v_add_f32_e32 v7, v7, v145
	v_add_f32_e32 v94, v94, v146
	v_add_f32_e32 v95, v95, v146
	v_add_f32_e32 v96, v96, v146
	v_add_f32_e32 v97, v97, v146
	v_exp_f32_e32 v4, v4
	v_exp_f32_e32 v5, v5
	v_exp_f32_e32 v6, v6
	v_exp_f32_e32 v7, v7
	v_exp_f32_e32 v94, v94
	v_exp_f32_e32 v95, v95
	v_exp_f32_e32 v96, v96
	v_exp_f32_e32 v97, v97
	v_add_f32_e32 v4, 1.0, v4
	v_add_f32_e32 v5, 1.0, v5
	v_add_f32_e32 v6, 1.0, v6
	v_add_f32_e32 v7, 1.0, v7
	v_add_f32_e32 v94, 1.0, v94
	v_add_f32_e32 v95, 1.0, v95
	v_add_f32_e32 v96, 1.0, v96
	v_add_f32_e32 v97, 1.0, v97
	v_rcp_f32_e32 v4, v4
	v_rcp_f32_e32 v5, v5
	v_rcp_f32_e32 v6, v6
	v_rcp_f32_e32 v7, v7
	v_rcp_f32_e32 v94, v94
	v_rcp_f32_e32 v95, v95
	v_rcp_f32_e32 v96, v96
	v_rcp_f32_e32 v97, v97
	v_mul_f32_e32 v4, v147, v4
	v_mul_f32_e32 v5, v147, v5
	v_mul_f32_e32 v6, v147, v6
	v_mul_f32_e32 v7, v147, v7
	v_mul_f32_e32 v94, v94, v166
	v_mul_f32_e32 v95, v95, v167
	v_mul_f32_e32 v96, v96, v168
	v_mul_f32_e32 v97, v97, v169
	v_exp_f32_e32 v4, v4
	v_exp_f32_e32 v5, v5
	v_exp_f32_e32 v6, v6
	v_exp_f32_e32 v7, v7
	s_nop 0
	v_fma_f32 v138, -v4, v4, 1.0 clamp
	v_fma_f32 v139, -v5, v5, 1.0 clamp
	v_fma_f32 v140, -v6, v6, 1.0 clamp
	v_fma_f32 v141, -v7, v7, 1.0 clamp
	v_sqrt_f32_e32 v138, v138
	v_sqrt_f32_e32 v139, v139
	v_sqrt_f32_e32 v140, v140
	v_sqrt_f32_e32 v141, v141
	s_nop 0
	v_mul_f32_e32 v94, v138, v94
	v_mul_f32_e32 v95, v139, v95
	v_mul_f32_e32 v96, v140, v96
	v_mul_f32_e32 v97, v141, v97
	v_add_f32_e32 v8, v8, v145
	v_add_f32_e32 v9, v9, v145
	v_add_f32_e32 v10, v10, v145
	v_add_f32_e32 v11, v11, v145
	v_add_f32_e32 v98, v98, v146
	v_add_f32_e32 v99, v99, v146
	v_add_f32_e32 v100, v100, v146
	v_add_f32_e32 v101, v101, v146
	v_exp_f32_e32 v8, v8
	v_exp_f32_e32 v9, v9
	v_exp_f32_e32 v10, v10
	v_exp_f32_e32 v11, v11
	v_exp_f32_e32 v98, v98
	v_exp_f32_e32 v99, v99
	v_exp_f32_e32 v100, v100
	v_exp_f32_e32 v101, v101
	v_add_f32_e32 v8, 1.0, v8
	v_add_f32_e32 v9, 1.0, v9
	v_add_f32_e32 v10, 1.0, v10
	v_add_f32_e32 v11, 1.0, v11
	v_add_f32_e32 v98, 1.0, v98
	v_add_f32_e32 v99, 1.0, v99
	v_add_f32_e32 v100, 1.0, v100
	v_add_f32_e32 v101, 1.0, v101
	v_rcp_f32_e32 v8, v8
	v_rcp_f32_e32 v9, v9
	v_rcp_f32_e32 v10, v10
	v_rcp_f32_e32 v11, v11
	v_rcp_f32_e32 v98, v98
	v_rcp_f32_e32 v99, v99
	v_rcp_f32_e32 v100, v100
	v_rcp_f32_e32 v101, v101
	v_mul_f32_e32 v8, v147, v8
	v_mul_f32_e32 v9, v147, v9
	v_mul_f32_e32 v10, v147, v10
	v_mul_f32_e32 v11, v147, v11
	v_mul_f32_e32 v98, v98, v170
	v_mul_f32_e32 v99, v99, v171
	v_mul_f32_e32 v100, v100, v172
	v_mul_f32_e32 v101, v101, v173
	v_exp_f32_e32 v8, v8
	v_exp_f32_e32 v9, v9
	v_exp_f32_e32 v10, v10
	v_exp_f32_e32 v11, v11
	s_nop 0
	v_fma_f32 v138, -v8, v8, 1.0 clamp
	v_fma_f32 v139, -v9, v9, 1.0 clamp
	v_fma_f32 v140, -v10, v10, 1.0 clamp
	v_fma_f32 v141, -v11, v11, 1.0 clamp
	v_sqrt_f32_e32 v138, v138
	v_sqrt_f32_e32 v139, v139
	v_sqrt_f32_e32 v140, v140
	v_sqrt_f32_e32 v141, v141
	s_nop 0
	v_mul_f32_e32 v98, v138, v98
	v_mul_f32_e32 v99, v139, v99
	v_mul_f32_e32 v100, v140, v100
	v_mul_f32_e32 v101, v141, v101
	v_add_f32_e32 v12, v12, v145
	v_add_f32_e32 v13, v13, v145
	v_add_f32_e32 v14, v14, v145
	v_add_f32_e32 v15, v15, v145
	v_add_f32_e32 v102, v102, v146
	v_add_f32_e32 v103, v103, v146
	v_add_f32_e32 v104, v104, v146
	v_add_f32_e32 v105, v105, v146
	v_exp_f32_e32 v12, v12
	v_exp_f32_e32 v13, v13
	v_exp_f32_e32 v14, v14
	v_exp_f32_e32 v15, v15
	v_exp_f32_e32 v102, v102
	v_exp_f32_e32 v103, v103
	v_exp_f32_e32 v104, v104
	v_exp_f32_e32 v105, v105
	v_add_f32_e32 v12, 1.0, v12
; __device__ __forceinline__ float bf2f(u16 h) { return __uint_as_float(((unsigned)h) << 16); }
; __device__ __forceinline__ void lru_tile(const Params& P, int chunk, int head, int pass, char* smem_raw) {
;     ...
; #pragma unroll
;       for (int tc = 0; tc < 4; ++tc)
; #pragma unroll
;         for (int reg = 0; reg < 4; ++reg) {
;           const int tl = wid * 16 + (lane >> 4) * 4 + reg;
;           const int c = 16 * tc + (lane & 15);
;           const float r = __builtin_amdgcn_rcpf(1.f + __builtin_amdgcn_exp2f(acc[tc][reg] + ba[tc]));
;           const float ii = __builtin_amdgcn_rcpf(1.f + __builtin_amdgcn_exp2f(acc[tc + 4][reg] + bi[tc]));
;           const float la = -c8[tc] * r;
;           const float a = __builtin_amdgcn_exp2f(la);
;           const float ucv = bf2f(sm_uc[(sb * 64 + tl) * LDSS + c]);
;           const float bt = __builtin_amdgcn_sqrtf(fmaxf(1.f - a * a, 0.f)) * (ii * ucv);
;           sm_a[tl * 64 + c] = a;
;           sm_b[tl * 64 + c] = bt;
;         }
	v_add_f32_e32 v13, 1.0, v13
	v_add_f32_e32 v14, 1.0, v14
	v_add_f32_e32 v15, 1.0, v15
	v_add_f32_e32 v102, 1.0, v102
	v_add_f32_e32 v103, 1.0, v103
	v_add_f32_e32 v104, 1.0, v104
	v_add_f32_e32 v105, 1.0, v105
	v_rcp_f32_e32 v12, v12
	v_rcp_f32_e32 v13, v13
	v_rcp_f32_e32 v14, v14
	v_rcp_f32_e32 v15, v15
	v_rcp_f32_e32 v102, v102
	v_rcp_f32_e32 v103, v103
	v_rcp_f32_e32 v104, v104
	v_rcp_f32_e32 v105, v105
	v_mul_f32_e32 v12, v147, v12
	v_mul_f32_e32 v13, v147, v13
	v_mul_f32_e32 v14, v147, v14
	v_mul_f32_e32 v15, v147, v15
	v_mul_f32_e32 v102, v102, v174
	v_mul_f32_e32 v103, v103, v175
	v_mul_f32_e32 v104, v104, v176
	v_mul_f32_e32 v105, v105, v177
	v_exp_f32_e32 v12, v12
	v_exp_f32_e32 v13, v13
	v_exp_f32_e32 v14, v14
	v_exp_f32_e32 v15, v15
	s_nop 0
	v_fma_f32 v138, -v12, v12, 1.0 clamp
	v_fma_f32 v139, -v13, v13, 1.0 clamp
	v_fma_f32 v140, -v14, v14, 1.0 clamp
	v_fma_f32 v141, -v15, v15, 1.0 clamp
	v_sqrt_f32_e32 v138, v138
	v_sqrt_f32_e32 v139, v139
	v_sqrt_f32_e32 v140, v140
	v_sqrt_f32_e32 v141, v141
	s_nop 0
	v_mul_f32_e32 v102, v138, v102
	v_mul_f32_e32 v103, v139, v103
	v_mul_f32_e32 v104, v140, v104
	v_mul_f32_e32 v105, v141, v105
	v_add_f32_e32 v16, v16, v145
	v_add_f32_e32 v17, v17, v145
	v_add_f32_e32 v18, v18, v145
	v_add_f32_e32 v19, v19, v145
	v_add_f32_e32 v106, v106, v146
	v_add_f32_e32 v107, v107, v146
	v_add_f32_e32 v108, v108, v146
	v_add_f32_e32 v109, v109, v146
	v_exp_f32_e32 v16, v16
	v_exp_f32_e32 v17, v17
	v_exp_f32_e32 v18, v18
	v_exp_f32_e32 v19, v19
	v_exp_f32_e32 v106, v106
	v_exp_f32_e32 v107, v107
	v_exp_f32_e32 v108, v108
	v_exp_f32_e32 v109, v109
	v_add_f32_e32 v16, 1.0, v16
	v_add_f32_e32 v17, 1.0, v17
	v_add_f32_e32 v18, 1.0, v18
	v_add_f32_e32 v19, 1.0, v19
	v_add_f32_e32 v106, 1.0, v106
	v_add_f32_e32 v107, 1.0, v107
	v_add_f32_e32 v108, 1.0, v108
	v_add_f32_e32 v109, 1.0, v109
	v_rcp_f32_e32 v16, v16
	v_rcp_f32_e32 v17, v17
	v_rcp_f32_e32 v18, v18
	v_rcp_f32_e32 v19, v19
	v_rcp_f32_e32 v106, v106
	v_rcp_f32_e32 v107, v107
	v_rcp_f32_e32 v108, v108
	v_rcp_f32_e32 v109, v109
	v_mul_f32_e32 v16, v147, v16
	v_mul_f32_e32 v17, v147, v17
	v_mul_f32_e32 v18, v147, v18
	v_mul_f32_e32 v19, v147, v19
	v_mul_f32_e32 v106, v106, v178
	v_mul_f32_e32 v107, v107, v179
	v_mul_f32_e32 v108, v108, v180
	v_mul_f32_e32 v109, v109, v181
	v_exp_f32_e32 v16, v16
	v_exp_f32_e32 v17, v17
	v_exp_f32_e32 v18, v18
	v_exp_f32_e32 v19, v19
	s_nop 0
	v_fma_f32 v138, -v16, v16, 1.0 clamp
	v_fma_f32 v139, -v17, v17, 1.0 clamp
	v_fma_f32 v140, -v18, v18, 1.0 clamp
	v_fma_f32 v141, -v19, v19, 1.0 clamp
	v_sqrt_f32_e32 v138, v138
	v_sqrt_f32_e32 v139, v139
	v_sqrt_f32_e32 v140, v140
	v_sqrt_f32_e32 v141, v141
	s_nop 0
	v_mul_f32_e32 v106, v138, v106
	v_mul_f32_e32 v107, v139, v107
	v_mul_f32_e32 v108, v140, v108
	v_mul_f32_e32 v109, v141, v109
	v_add_f32_e32 v20, v20, v145
	v_add_f32_e32 v21, v21, v145
	v_add_f32_e32 v22, v22, v145
	v_add_f32_e32 v23, v23, v145
	v_add_f32_e32 v110, v110, v146
	v_add_f32_e32 v111, v111, v146
	v_add_f32_e32 v112, v112, v146
	v_add_f32_e32 v113, v113, v146
	v_exp_f32_e32 v20, v20
	v_exp_f32_e32 v21, v21
	v_exp_f32_e32 v22, v22
	v_exp_f32_e32 v23, v23
	v_exp_f32_e32 v110, v110
	v_exp_f32_e32 v111, v111
	v_exp_f32_e32 v112, v112
	v_exp_f32_e32 v113, v113
	v_add_f32_e32 v20, 1.0, v20
	v_add_f32_e32 v21, 1.0, v21
	v_add_f32_e32 v22, 1.0, v22
	v_add_f32_e32 v23, 1.0, v23
	v_add_f32_e32 v110, 1.0, v110
	v_add_f32_e32 v111, 1.0, v111
	v_add_f32_e32 v112, 1.0, v112
	v_add_f32_e32 v113, 1.0, v113
	v_rcp_f32_e32 v20, v20
	v_rcp_f32_e32 v21, v21
	v_rcp_f32_e32 v22, v22
	v_rcp_f32_e32 v23, v23
	v_rcp_f32_e32 v110, v110
	v_rcp_f32_e32 v111, v111
	v_rcp_f32_e32 v112, v112
	v_rcp_f32_e32 v113, v113
	v_mul_f32_e32 v20, v147, v20
	v_mul_f32_e32 v21, v147, v21
	v_mul_f32_e32 v22, v147, v22
	v_mul_f32_e32 v23, v147, v23
	v_mul_f32_e32 v110, v110, v182
	v_mul_f32_e32 v111, v111, v183
	v_mul_f32_e32 v112, v112, v184
	v_mul_f32_e32 v113, v113, v185
	v_exp_f32_e32 v20, v20
	v_exp_f32_e32 v21, v21
	v_exp_f32_e32 v22, v22
	v_exp_f32_e32 v23, v23
	s_nop 0
	v_fma_f32 v138, -v20, v20, 1.0 clamp
	v_fma_f32 v139, -v21, v21, 1.0 clamp
	v_fma_f32 v140, -v22, v22, 1.0 clamp
	v_fma_f32 v141, -v23, v23, 1.0 clamp
	v_sqrt_f32_e32 v138, v138
	v_sqrt_f32_e32 v139, v139
	v_sqrt_f32_e32 v140, v140
	v_sqrt_f32_e32 v141, v141
	s_nop 0
	v_mul_f32_e32 v110, v138, v110
	v_mul_f32_e32 v111, v139, v111
	v_mul_f32_e32 v112, v140, v112
	v_mul_f32_e32 v113, v141, v113
	v_add_f32_e32 v24, v24, v145
	v_add_f32_e32 v25, v25, v145
	v_add_f32_e32 v26, v26, v145
	v_add_f32_e32 v27, v27, v145
	v_add_f32_e32 v114, v114, v146
	v_add_f32_e32 v115, v115, v146
	v_add_f32_e32 v116, v116, v146
	v_add_f32_e32 v117, v117, v146
	v_exp_f32_e32 v24, v24
	v_exp_f32_e32 v25, v25
	v_exp_f32_e32 v26, v26
	v_exp_f32_e32 v27, v27
	v_exp_f32_e32 v114, v114
	v_exp_f32_e32 v115, v115
	v_exp_f32_e32 v116, v116
	v_exp_f32_e32 v117, v117
	v_add_f32_e32 v24, 1.0, v24
	v_add_f32_e32 v25, 1.0, v25
	v_add_f32_e32 v26, 1.0, v26
	v_add_f32_e32 v27, 1.0, v27
	v_add_f32_e32 v114, 1.0, v114
	v_add_f32_e32 v115, 1.0, v115
	v_add_f32_e32 v116, 1.0, v116
	v_add_f32_e32 v117, 1.0, v117
	v_rcp_f32_e32 v24, v24
	v_rcp_f32_e32 v25, v25
	v_rcp_f32_e32 v26, v26
	v_rcp_f32_e32 v27, v27
	v_rcp_f32_e32 v114, v114
	v_rcp_f32_e32 v115, v115
	v_rcp_f32_e32 v116, v116
	v_rcp_f32_e32 v117, v117
	v_mul_f32_e32 v24, v147, v24
	v_mul_f32_e32 v25, v147, v25
	v_mul_f32_e32 v26, v147, v26
	v_mul_f32_e32 v27, v147, v27
; __device__ __forceinline__ float bf2f(u16 h) { return __uint_as_float(((unsigned)h) << 16); }
; __device__ __forceinline__ void lru_tile(const Params& P, int chunk, int head, int pass, char* smem_raw) {
;     ...
;         float Pp = 1.f, H = 0.f;
; #pragma unroll 4
;         for (int i = 0; i < 16; ++i) {
;           const int tl = (d == 0) ? (q * 16 + i) : (q * 16 + 15 - i);
;           const float a = sm_a[tl * 64 + ch], b = sm_b[tl * 64 + ch];
;           H = a * H + b; Pp *= a;
;         }
;         sm_ph[pos * 64 + ch] = make_float2(Pp, H);
;       }
;       __syncthreads();
;       const float2 p0 = sm_ph[ch], p1 = sm_ph[64 + ch], p2 = sm_ph[128 + ch], p3 = sm_ph[192 + ch];
;       if (pass == 2) {
;         float hin = cB;
;         if (pos > 0) hin = p0.x * hin + p0.y;
;         if (pos > 1) hin = p1.x * hin + p1.y;
;         if (pos > 2) hin = p2.x * hin + p2.y;
;         float h = hin;
;         float hfp[16], gp[16];
;         if (d == 1) {
; #pragma unroll
;           for (int i = 0; i < 16; ++i) {
;             const long rowp = row0 + sb * 64 + q * 16 + 15 - i;
;             hfp[i] = hfbuf[rowp * 512 + gch];
;             gp[i] = bf2f(P.zq[rowp * 1536 + 512 + gch]);
;           }
;         }
; #pragma unroll
;         for (int i = 0; i < 16; ++i) {
;           const int tl = (d == 0) ? (q * 16 + i) : (q * 16 + 15 - i);
;           const float a = sm_a[tl * 64 + ch], b = sm_b[tl * 64 + ch];
;           h = a * h + b;
;           const long row = row0 + sb * 64 + tl;
;           if (d == 0) {
;             hfw[row * 512 + gch] = h;
;           } else {
;             const float hfv = hfp[i];
;             const float g = gp[i];
;             const float tz = 0.7978845608028654f * (g + 0.044715f * g * g * g);
;             const float th = 1.f - 2.f * __builtin_amdgcn_rcpf(1.f + __expf(2.f * tz));
;             const float ge = 0.5f * g * (1.f + th);
;             P.cat[row * 1024 + gch] = f2bf((hfv + h) * ge);
;           }
;         }
;       }
;       cB = p0.x * cB + p0.y; cA *= p0.x;
;       cB = p1.x * cB + p1.y; cA *= p1.x;
;       cB = p2.x * cB + p2.y; cA *= p2.x;
;       cB = p3.x * cB + p3.y; cA *= p3.x;
;       __syncthreads();
;     }
;     if (pass == 1 && q == 0) P.summ[((long)d * 264 + chunk) * 512 + gch] = make_float2(cA, cB);
	v_mul_f32_e32 v114, v114, v186
	v_mul_f32_e32 v115, v115, v187
	v_mul_f32_e32 v116, v116, v188
	v_mul_f32_e32 v117, v117, v189
	v_exp_f32_e32 v24, v24
	v_exp_f32_e32 v25, v25
	v_exp_f32_e32 v26, v26
	v_exp_f32_e32 v27, v27
	s_nop 0
	v_fma_f32 v138, -v24, v24, 1.0 clamp
	v_fma_f32 v139, -v25, v25, 1.0 clamp
	v_fma_f32 v140, -v26, v26, 1.0 clamp
	v_fma_f32 v141, -v27, v27, 1.0 clamp
	v_sqrt_f32_e32 v138, v138
	v_sqrt_f32_e32 v139, v139
	v_sqrt_f32_e32 v140, v140
	v_sqrt_f32_e32 v141, v141
	s_nop 0
	v_mul_f32_e32 v114, v138, v114
	v_mul_f32_e32 v115, v139, v115
	v_mul_f32_e32 v116, v140, v116
	v_mul_f32_e32 v117, v141, v117
	v_add_f32_e32 v28, v28, v145
	v_add_f32_e32 v29, v29, v145
	v_add_f32_e32 v30, v30, v145
	v_add_f32_e32 v31, v31, v145
	v_add_f32_e32 v118, v118, v146
	v_add_f32_e32 v119, v119, v146
	v_add_f32_e32 v120, v120, v146
	v_add_f32_e32 v121, v121, v146
	v_exp_f32_e32 v28, v28
	v_exp_f32_e32 v29, v29
	v_exp_f32_e32 v30, v30
	v_exp_f32_e32 v31, v31
	v_exp_f32_e32 v118, v118
	v_exp_f32_e32 v119, v119
	v_exp_f32_e32 v120, v120
	v_exp_f32_e32 v121, v121
	v_add_f32_e32 v28, 1.0, v28
	v_add_f32_e32 v29, 1.0, v29
	v_add_f32_e32 v30, 1.0, v30
	v_add_f32_e32 v31, 1.0, v31
	v_add_f32_e32 v118, 1.0, v118
	v_add_f32_e32 v119, 1.0, v119
	v_add_f32_e32 v120, 1.0, v120
	v_add_f32_e32 v121, 1.0, v121
	v_rcp_f32_e32 v28, v28
	v_rcp_f32_e32 v29, v29
	v_rcp_f32_e32 v30, v30
	v_rcp_f32_e32 v31, v31
	v_rcp_f32_e32 v118, v118
	v_rcp_f32_e32 v119, v119
	v_rcp_f32_e32 v120, v120
	v_rcp_f32_e32 v121, v121
	v_mul_f32_e32 v28, v147, v28
	v_mul_f32_e32 v29, v147, v29
	v_mul_f32_e32 v30, v147, v30
	v_mul_f32_e32 v31, v147, v31
	v_mul_f32_e32 v118, v118, v190
	v_mul_f32_e32 v119, v119, v191
	v_mul_f32_e32 v120, v120, v192
	v_mul_f32_e32 v121, v121, v193
	v_exp_f32_e32 v28, v28
	v_exp_f32_e32 v29, v29
	v_exp_f32_e32 v30, v30
	v_exp_f32_e32 v31, v31
	s_nop 0
	v_fma_f32 v138, -v28, v28, 1.0 clamp
	v_fma_f32 v139, -v29, v29, 1.0 clamp
	v_fma_f32 v140, -v30, v30, 1.0 clamp
	v_fma_f32 v141, -v31, v31, 1.0 clamp
	v_sqrt_f32_e32 v138, v138
	v_sqrt_f32_e32 v139, v139
	v_sqrt_f32_e32 v140, v140
	v_sqrt_f32_e32 v141, v141
	s_nop 0
	v_mul_f32_e32 v118, v138, v118
	v_mul_f32_e32 v119, v139, v119
	v_mul_f32_e32 v120, v140, v120
	v_mul_f32_e32 v121, v141, v121
	v_mov_b32_e32 v253, v31
	v_mov_b32_e32 v254, v121
	v_fma_f32 v254, v30, v254, v120
	v_mul_f32_e32 v253, v253, v30
	v_fma_f32 v254, v29, v254, v119
	v_mul_f32_e32 v253, v253, v29
	v_fma_f32 v254, v28, v254, v118
	v_mul_f32_e32 v253, v253, v28
	v_fma_f32 v254, v27, v254, v117
	v_mul_f32_e32 v253, v253, v27
	v_fma_f32 v254, v26, v254, v116
	v_mul_f32_e32 v253, v253, v26
	v_fma_f32 v254, v25, v254, v115
	v_mul_f32_e32 v253, v253, v25
	v_fma_f32 v254, v24, v254, v114
	v_mul_f32_e32 v253, v253, v24
	v_fma_f32 v254, v23, v254, v113
	v_mul_f32_e32 v253, v253, v23
	v_fma_f32 v254, v22, v254, v112
	v_mul_f32_e32 v253, v253, v22
	v_fma_f32 v254, v21, v254, v111
	v_mul_f32_e32 v253, v253, v21
	v_fma_f32 v254, v20, v254, v110
	v_mul_f32_e32 v253, v253, v20
	v_fma_f32 v254, v19, v254, v109
	v_mul_f32_e32 v253, v253, v19
	v_fma_f32 v254, v18, v254, v108
	v_mul_f32_e32 v253, v253, v18
	v_fma_f32 v254, v17, v254, v107
	v_mul_f32_e32 v253, v253, v17
	v_fma_f32 v254, v16, v254, v106
	v_mul_f32_e32 v253, v253, v16
	v_fma_f32 v254, v15, v254, v105
	v_mul_f32_e32 v253, v253, v15
	v_fma_f32 v254, v14, v254, v104
	v_mul_f32_e32 v253, v253, v14
	v_fma_f32 v254, v13, v254, v103
	v_mul_f32_e32 v253, v253, v13
	v_fma_f32 v254, v12, v254, v102
	v_mul_f32_e32 v253, v253, v12
	v_fma_f32 v254, v11, v254, v101
	v_mul_f32_e32 v253, v253, v11
	v_fma_f32 v254, v10, v254, v100
	v_mul_f32_e32 v253, v253, v10
	v_fma_f32 v254, v9, v254, v99
	v_mul_f32_e32 v253, v253, v9
	v_fma_f32 v254, v8, v254, v98
	v_mul_f32_e32 v253, v253, v8
	v_fma_f32 v254, v7, v254, v97
	v_mul_f32_e32 v253, v253, v7
	v_fma_f32 v254, v6, v254, v96
	v_mul_f32_e32 v253, v253, v6
	v_fma_f32 v254, v5, v254, v95
	v_mul_f32_e32 v253, v253, v5
	v_fma_f32 v254, v4, v254, v94
	v_mul_f32_e32 v253, v253, v4
	v_fma_f32 v254, v3, v254, v93
	v_mul_f32_e32 v253, v253, v3
	v_fma_f32 v254, v2, v254, v92
	v_mul_f32_e32 v253, v253, v2
	v_fma_f32 v254, v1, v254, v91
	v_mul_f32_e32 v253, v253, v1
	v_fma_f32 v254, v0, v254, v90
	v_mul_f32_e32 v253, v253, v0
	v_mov_b32_e32 v138, v253
	v_mov_b32_e32 v139, v253
	s_nop 1
	v_permlane16_swap_b32_e32 v138, v139
	v_mov_b32_e32 v140, v138
	v_mov_b32_e32 v141, v139
	s_nop 1
	v_permlane32_swap_b32_e32 v138, v140
	v_permlane32_swap_b32_e32 v139, v141
	v_mov_b32_e32 v198, v254
	v_mov_b32_e32 v199, v254
	s_nop 1
	v_permlane16_swap_b32_e32 v198, v199
	v_mov_b32_e32 v200, v198
	v_mov_b32_e32 v201, v199
	s_nop 1
	v_permlane32_swap_b32_e32 v198, v200
	v_permlane32_swap_b32_e32 v199, v201
	v_mov_b32_e32 v202, 0
	v_fma_f32 v151, v141, v202, v201
	v_fma_f32 v150, v140, v151, v200
	v_fma_f32 v136, v139, v150, v199
	v_fma_f32 v254, v138, v136, v198
	v_mul_f32_e32 v253, v138, v139
	v_mul_f32_e32 v253, v253, v140
	v_mul_f32_e32 v200, v253, v141
	v_mov_b32_e32 v201, v254
	s_add_u32 s0, s71, 264
	s_lshl_b32 s0, s0, 12
	s_lshl_b32 s1, s56, 3
	s_add_u32 s0, s0, s1
	s_add_u32 s4, s18, s0
	s_addc_u32 s5, s19, 0
	global_store_dwordx2 v250, v[200:201], s[4:5]
	v_add_u32_e32 v89, s62, v89
	v_add_u32_e32 v130, s62, v130
	v_add_u32_e32 v131, s62, v131
	v_add_u32_e32 v133, s62, v133
	s_sub_u32 s62, 0, s62
	s_add_u32 s69, s69, 1
	s_cmp_lt_u32 s69, s70
	s_cbranch_scc1 .Lmy_lrua_tile
	s_waitcnt lgkmcnt(0)
	s_barrier

; __device__ __forceinline__ void lru_tile(const Params& P, int chunk, int head, int pass, char* smem_raw) {
;     ...
;       *reinterpret_cast<uint4*>(&sm_w[rowi * LDSS + kg * 8]) = ldg16(P.wg + ((long)(d * 8 + head) * 128 + rowi) * 64 + kg * 8);
;     }
;     float ba[4], bi[4], c8[4];
; #pragma unroll
;     for (int tc = 0; tc < 4; ++tc) {
;       const int cidx = d * 512 + head * 64 + 16 * tc + (lane & 15);
;       ba[tc] = P.b_a[cidx] * -1.4426950408889634f; bi[tc] = P.b_i[cidx] * -1.4426950408889634f;
;       const float nl = -P.lam[cidx];
;       const float e_ = __expf(nl);
;       const float sp = (nl > 20.f) ? nl
;                      : (e_ < 0.03f ? e_ * (1.f - e_ * (0.5f - e_ * (0.33333334f - 0.25f * e_))) : __logf(1.f + e_));
;       c8[tc] = 8.f * 1.4426950408889634f * sp;
;     }
;     __syncthreads();
;     float cA = 1.f, cB = (pass == 2) ? sm_init[d * 64 + ch] : 0.f;
;     for (int sbi = 0; sbi < 2; ++sbi) {
;       const int sb = (d == 0) ? sbi : 1 - sbi;
;       f32x4 acc[8];
; #pragma unroll
;       for (int t = 0; t < 8; ++t) acc[t] = f32x4{0.f, 0.f, 0.f, 0.f};
; #pragma unroll
;       for (int s = 0; s < 2; ++s) {
;         const bf16x8 af = *reinterpret_cast<const bf16x8*>(&sm_uc[(sb * 64 + wid * 16 + (lane & 15)) * LDSS + s * 32 + (lane >> 4) * 8]);
; #pragma unroll
;         for (int t = 0; t < 8; ++t) {
;           const bf16x8 bfr = *reinterpret_cast<const bf16x8*>(&sm_w[(t * 16 + (lane & 15)) * LDSS + s * 32 + (lane >> 4) * 8]);
;           acc[t] = __builtin_amdgcn_mfma_f32_16x16x32_bf16(af, bfr, acc[t], 0, 0, 0);
;         }
;       }
; #pragma unroll
;       for (int tc = 0; tc < 4; ++tc)
; #pragma unroll
;         for (int reg = 0; reg < 4; ++reg) {
;           const int tl = wid * 16 + (lane >> 4) * 4 + reg;
;           const int c = 16 * tc + (lane & 15);
;           const float r = __builtin_amdgcn_rcpf(1.f + __builtin_amdgcn_exp2f(acc[tc][reg] + ba[tc]));
;           const float ii = __builtin_amdgcn_rcpf(1.f + __builtin_amdgcn_exp2f(acc[tc + 4][reg] + bi[tc]));
;           const float la = -c8[tc] * r;
;           const float a = __builtin_amdgcn_exp2f(la);
;           const float ucv = bf2f(sm_uc[(sb * 64 + tl) * LDSS + c]);
;           const float bt = __builtin_amdgcn_sqrtf(fmaxf(1.f - a * a, 0.f)) * (ii * ucv);
;           sm_a[tl * 64 + c] = a;
;           sm_b[tl * 64 + c] = bt;
;         }
.Lmy_lrub_nopf:
	ds_read_b128 v[76:79], v131 offset:0
	ds_read_b128 v[80:83], v133 offset:0
	ds_read_b128 v[122:125], v131 offset:512
	ds_read_b128 v[126:129], v133 offset:512
	s_waitcnt lgkmcnt(3)
	v_mfma_f32_16x16x32_bf16 v[0:3], v[76:79], v[238:241], 0
	v_mfma_f32_16x16x32_bf16 v[90:93], v[76:79], v[246:249], 0
	ds_read_b128 v[76:79], v131 offset:1024
	s_waitcnt lgkmcnt(3)
	v_mfma_f32_16x16x32_bf16 v[0:3], v[80:83], v[242:245], v[0:3]
	v_mfma_f32_16x16x32_bf16 v[90:93], v[80:83], v[194:197], v[90:93]
	ds_read_b128 v[80:83], v133 offset:1024
	s_waitcnt lgkmcnt(3)
	v_mfma_f32_16x16x32_bf16 v[4:7], v[122:125], v[238:241], 0
	v_mfma_f32_16x16x32_bf16 v[94:97], v[122:125], v[246:249], 0
	ds_read_b128 v[122:125], v131 offset:1536
	s_waitcnt lgkmcnt(3)
	v_mfma_f32_16x16x32_bf16 v[4:7], v[126:129], v[242:245], v[4:7]
	v_mfma_f32_16x16x32_bf16 v[94:97], v[126:129], v[194:197], v[94:97]
	ds_read_b128 v[126:129], v133 offset:1536
	s_waitcnt lgkmcnt(3)
	v_mfma_f32_16x16x32_bf16 v[8:11], v[76:79], v[238:241], 0
	v_mfma_f32_16x16x32_bf16 v[98:101], v[76:79], v[246:249], 0
	ds_read_b128 v[76:79], v131 offset:2048
	s_waitcnt lgkmcnt(3)
	v_mfma_f32_16x16x32_bf16 v[8:11], v[80:83], v[242:245], v[8:11]
	v_mfma_f32_16x16x32_bf16 v[98:101], v[80:83], v[194:197], v[98:101]
	ds_read_b128 v[80:83], v133 offset:2048
	s_waitcnt lgkmcnt(3)
	v_mfma_f32_16x16x32_bf16 v[12:15], v[122:125], v[238:241], 0
	v_mfma_f32_16x16x32_bf16 v[102:105], v[122:125], v[246:249], 0
	ds_read_b128 v[122:125], v131 offset:2560
	s_waitcnt lgkmcnt(3)
	v_mfma_f32_16x16x32_bf16 v[12:15], v[126:129], v[242:245], v[12:15]
	v_mfma_f32_16x16x32_bf16 v[102:105], v[126:129], v[194:197], v[102:105]
	ds_read_b128 v[126:129], v133 offset:2560
	s_waitcnt lgkmcnt(3)
	v_mfma_f32_16x16x32_bf16 v[16:19], v[76:79], v[238:241], 0
	v_mfma_f32_16x16x32_bf16 v[106:109], v[76:79], v[246:249], 0
	ds_read_b128 v[76:79], v131 offset:3072
	s_waitcnt lgkmcnt(3)
	v_mfma_f32_16x16x32_bf16 v[16:19], v[80:83], v[242:245], v[16:19]
	v_mfma_f32_16x16x32_bf16 v[106:109], v[80:83], v[194:197], v[106:109]
	ds_read_b128 v[80:83], v133 offset:3072
	s_waitcnt lgkmcnt(3)
	v_mfma_f32_16x16x32_bf16 v[20:23], v[122:125], v[238:241], 0
	v_mfma_f32_16x16x32_bf16 v[110:113], v[122:125], v[246:249], 0
	ds_read_b128 v[122:125], v131 offset:3584
	s_waitcnt lgkmcnt(3)
	v_mfma_f32_16x16x32_bf16 v[20:23], v[126:129], v[242:245], v[20:23]
	v_mfma_f32_16x16x32_bf16 v[110:113], v[126:129], v[194:197], v[110:113]
	ds_read_b128 v[126:129], v133 offset:3584
	s_waitcnt lgkmcnt(3)
	v_mfma_f32_16x16x32_bf16 v[24:27], v[76:79], v[238:241], 0
	v_mfma_f32_16x16x32_bf16 v[114:117], v[76:79], v[246:249], 0
	s_waitcnt lgkmcnt(2)
	v_mfma_f32_16x16x32_bf16 v[24:27], v[80:83], v[242:245], v[24:27]
	v_mfma_f32_16x16x32_bf16 v[114:117], v[80:83], v[194:197], v[114:117]
	s_waitcnt lgkmcnt(1)
	v_mfma_f32_16x16x32_bf16 v[28:31], v[122:125], v[238:241], 0
	v_mfma_f32_16x16x32_bf16 v[118:121], v[122:125], v[246:249], 0
	s_waitcnt lgkmcnt(0)
	v_mfma_f32_16x16x32_bf16 v[28:31], v[126:129], v[242:245], v[28:31]
	v_mfma_f32_16x16x32_bf16 v[118:121], v[126:129], v[194:197], v[118:121]
	s_lshl_b32 s0, s56, 8
	s_add_u32 s0, s0, 0x20000
	s_add_u32 s4, s20, s0
	s_addc_u32 s5, s21, 0
	global_load_dwordx4 v[238:241], v251, s[4:5]
	global_load_dwordx4 v[242:245], v251, s[4:5] offset:64
	s_add_u32 s4, s4, 0x2000
	s_addc_u32 s5, s5, 0
	global_load_dwordx4 v[246:249], v251, s[4:5]
	global_load_dwordx4 v[194:197], v251, s[4:5] offset:64
	s_nop 7
	s_nop 7
	v_add_f32_e32 v0, v0, v75
	v_add_f32_e32 v1, v1, v75
	v_add_f32_e32 v2, v2, v75
	v_add_f32_e32 v3, v3, v75
	v_add_f32_e32 v90, v90, v84
	v_add_f32_e32 v91, v91, v84
	v_add_f32_e32 v92, v92, v84
	v_add_f32_e32 v93, v93, v84
	v_exp_f32_e32 v0, v0
	v_exp_f32_e32 v1, v1
	v_exp_f32_e32 v2, v2
	v_exp_f32_e32 v3, v3
	v_exp_f32_e32 v90, v90
	v_exp_f32_e32 v91, v91
	v_exp_f32_e32 v92, v92
	v_exp_f32_e32 v93, v93
	v_add_f32_e32 v0, 1.0, v0
	v_add_f32_e32 v1, 1.0, v1
	v_add_f32_e32 v2, 1.0, v2
	v_add_f32_e32 v3, 1.0, v3
	v_add_f32_e32 v90, 1.0, v90
	v_add_f32_e32 v91, 1.0, v91
	v_add_f32_e32 v92, 1.0, v92
	v_add_f32_e32 v93, 1.0, v93
	v_rcp_f32_e32 v0, v0
	v_rcp_f32_e32 v1, v1
	v_rcp_f32_e32 v2, v2
	v_rcp_f32_e32 v3, v3
	v_rcp_f32_e32 v90, v90
	v_rcp_f32_e32 v91, v91
	v_rcp_f32_e32 v92, v92
	v_rcp_f32_e32 v93, v93
	v_mul_f32_e32 v0, v85, v0
	v_mul_f32_e32 v1, v85, v1
	v_mul_f32_e32 v2, v85, v2
	v_mul_f32_e32 v3, v85, v3
	v_mul_f32_e32 v90, v90, v162
	v_mul_f32_e32 v91, v91, v163
	v_mul_f32_e32 v92, v92, v164
	v_mul_f32_e32 v93, v93, v165
	v_exp_f32_e32 v0, v0
	v_exp_f32_e32 v1, v1
	v_exp_f32_e32 v2, v2
	v_exp_f32_e32 v3, v3
	s_nop 0
	v_fma_f32 v138, -v0, v0, 1.0 clamp
	v_fma_f32 v139, -v1, v1, 1.0 clamp
	v_fma_f32 v140, -v2, v2, 1.0 clamp
	v_fma_f32 v141, -v3, v3, 1.0 clamp
	v_sqrt_f32_e32 v138, v138
	v_sqrt_f32_e32 v139, v139
	v_sqrt_f32_e32 v140, v140
	v_sqrt_f32_e32 v141, v141
	s_nop 0
	v_mul_f32_e32 v90, v138, v90
	v_mul_f32_e32 v91, v139, v91
	v_mul_f32_e32 v92, v140, v92
	v_mul_f32_e32 v93, v141, v93
	v_add_f32_e32 v4, v4, v75
	v_add_f32_e32 v5, v5, v75
	v_add_f32_e32 v6, v6, v75
	v_add_f32_e32 v7, v7, v75
	v_add_f32_e32 v94, v94, v84
	v_add_f32_e32 v95, v95, v84
	v_add_f32_e32 v96, v96, v84
	v_add_f32_e32 v97, v97, v84
	v_exp_f32_e32 v4, v4
	v_exp_f32_e32 v5, v5
	v_exp_f32_e32 v6, v6
	v_exp_f32_e32 v7, v7
	v_exp_f32_e32 v94, v94
	v_exp_f32_e32 v95, v95
	v_exp_f32_e32 v96, v96
	v_exp_f32_e32 v97, v97
	v_add_f32_e32 v4, 1.0, v4
	v_add_f32_e32 v5, 1.0, v5
	v_add_f32_e32 v6, 1.0, v6
	v_add_f32_e32 v7, 1.0, v7
	v_add_f32_e32 v94, 1.0, v94
	v_add_f32_e32 v95, 1.0, v95
	v_add_f32_e32 v96, 1.0, v96
	v_add_f32_e32 v97, 1.0, v97
; __device__ __forceinline__ float bf2f(u16 h) { return __uint_as_float(((unsigned)h) << 16); }
; __device__ __forceinline__ void lru_tile(const Params& P, int chunk, int head, int pass, char* smem_raw) {
;     ...
; #pragma unroll
;       for (int tc = 0; tc < 4; ++tc)
; #pragma unroll
;         for (int reg = 0; reg < 4; ++reg) {
;           const int tl = wid * 16 + (lane >> 4) * 4 + reg;
;           const int c = 16 * tc + (lane & 15);
;           const float r = __builtin_amdgcn_rcpf(1.f + __builtin_amdgcn_exp2f(acc[tc][reg] + ba[tc]));
;           const float ii = __builtin_amdgcn_rcpf(1.f + __builtin_amdgcn_exp2f(acc[tc + 4][reg] + bi[tc]));
;           const float la = -c8[tc] * r;
;           const float a = __builtin_amdgcn_exp2f(la);
;           const float ucv = bf2f(sm_uc[(sb * 64 + tl) * LDSS + c]);
;           const float bt = __builtin_amdgcn_sqrtf(fmaxf(1.f - a * a, 0.f)) * (ii * ucv);
;           sm_a[tl * 64 + c] = a;
;           sm_b[tl * 64 + c] = bt;
;         }
	v_rcp_f32_e32 v4, v4
	v_rcp_f32_e32 v5, v5
	v_rcp_f32_e32 v6, v6
	v_rcp_f32_e32 v7, v7
	v_rcp_f32_e32 v94, v94
	v_rcp_f32_e32 v95, v95
	v_rcp_f32_e32 v96, v96
	v_rcp_f32_e32 v97, v97
	v_mul_f32_e32 v4, v85, v4
	v_mul_f32_e32 v5, v85, v5
	v_mul_f32_e32 v6, v85, v6
	v_mul_f32_e32 v7, v85, v7
	v_mul_f32_e32 v94, v94, v166
	v_mul_f32_e32 v95, v95, v167
	v_mul_f32_e32 v96, v96, v168
	v_mul_f32_e32 v97, v97, v169
	v_exp_f32_e32 v4, v4
	v_exp_f32_e32 v5, v5
	v_exp_f32_e32 v6, v6
	v_exp_f32_e32 v7, v7
	s_nop 0
	v_fma_f32 v138, -v4, v4, 1.0 clamp
	v_fma_f32 v139, -v5, v5, 1.0 clamp
	v_fma_f32 v140, -v6, v6, 1.0 clamp
	v_fma_f32 v141, -v7, v7, 1.0 clamp
	v_sqrt_f32_e32 v138, v138
	v_sqrt_f32_e32 v139, v139
	v_sqrt_f32_e32 v140, v140
	v_sqrt_f32_e32 v141, v141
	s_nop 0
	v_mul_f32_e32 v94, v138, v94
	v_mul_f32_e32 v95, v139, v95
	v_mul_f32_e32 v96, v140, v96
	v_mul_f32_e32 v97, v141, v97
	v_add_f32_e32 v8, v8, v75
	v_add_f32_e32 v9, v9, v75
	v_add_f32_e32 v10, v10, v75
	v_add_f32_e32 v11, v11, v75
	v_add_f32_e32 v98, v98, v84
	v_add_f32_e32 v99, v99, v84
	v_add_f32_e32 v100, v100, v84
	v_add_f32_e32 v101, v101, v84
	v_exp_f32_e32 v8, v8
	v_exp_f32_e32 v9, v9
	v_exp_f32_e32 v10, v10
	v_exp_f32_e32 v11, v11
	v_exp_f32_e32 v98, v98
	v_exp_f32_e32 v99, v99
	v_exp_f32_e32 v100, v100
	v_exp_f32_e32 v101, v101
	v_add_f32_e32 v8, 1.0, v8
	v_add_f32_e32 v9, 1.0, v9
	v_add_f32_e32 v10, 1.0, v10
	v_add_f32_e32 v11, 1.0, v11
	v_add_f32_e32 v98, 1.0, v98
	v_add_f32_e32 v99, 1.0, v99
	v_add_f32_e32 v100, 1.0, v100
	v_add_f32_e32 v101, 1.0, v101
	v_rcp_f32_e32 v8, v8
	v_rcp_f32_e32 v9, v9
	v_rcp_f32_e32 v10, v10
	v_rcp_f32_e32 v11, v11
	v_rcp_f32_e32 v98, v98
	v_rcp_f32_e32 v99, v99
	v_rcp_f32_e32 v100, v100
	v_rcp_f32_e32 v101, v101
	v_mul_f32_e32 v8, v85, v8
	v_mul_f32_e32 v9, v85, v9
	v_mul_f32_e32 v10, v85, v10
	v_mul_f32_e32 v11, v85, v11
	v_mul_f32_e32 v98, v98, v170
	v_mul_f32_e32 v99, v99, v171
	v_mul_f32_e32 v100, v100, v172
	v_mul_f32_e32 v101, v101, v173
	v_exp_f32_e32 v8, v8
	v_exp_f32_e32 v9, v9
	v_exp_f32_e32 v10, v10
	v_exp_f32_e32 v11, v11
	s_nop 0
	v_fma_f32 v138, -v8, v8, 1.0 clamp
	v_fma_f32 v139, -v9, v9, 1.0 clamp
	v_fma_f32 v140, -v10, v10, 1.0 clamp
	v_fma_f32 v141, -v11, v11, 1.0 clamp
	v_sqrt_f32_e32 v138, v138
	v_sqrt_f32_e32 v139, v139
	v_sqrt_f32_e32 v140, v140
	v_sqrt_f32_e32 v141, v141
	s_nop 0
	v_mul_f32_e32 v98, v138, v98
	v_mul_f32_e32 v99, v139, v99
	v_mul_f32_e32 v100, v140, v100
	v_mul_f32_e32 v101, v141, v101
	v_add_f32_e32 v12, v12, v75
	v_add_f32_e32 v13, v13, v75
	v_add_f32_e32 v14, v14, v75
	v_add_f32_e32 v15, v15, v75
	v_add_f32_e32 v102, v102, v84
	v_add_f32_e32 v103, v103, v84
	v_add_f32_e32 v104, v104, v84
	v_add_f32_e32 v105, v105, v84
	v_exp_f32_e32 v12, v12
	v_exp_f32_e32 v13, v13
	v_exp_f32_e32 v14, v14
	v_exp_f32_e32 v15, v15
	v_exp_f32_e32 v102, v102
	v_exp_f32_e32 v103, v103
	v_exp_f32_e32 v104, v104
	v_exp_f32_e32 v105, v105
	v_add_f32_e32 v12, 1.0, v12
	v_add_f32_e32 v13, 1.0, v13
	v_add_f32_e32 v14, 1.0, v14
	v_add_f32_e32 v15, 1.0, v15
	v_add_f32_e32 v102, 1.0, v102
	v_add_f32_e32 v103, 1.0, v103
	v_add_f32_e32 v104, 1.0, v104
	v_add_f32_e32 v105, 1.0, v105
	v_rcp_f32_e32 v12, v12
	v_rcp_f32_e32 v13, v13
	v_rcp_f32_e32 v14, v14
	v_rcp_f32_e32 v15, v15
	v_rcp_f32_e32 v102, v102
	v_rcp_f32_e32 v103, v103
	v_rcp_f32_e32 v104, v104
	v_rcp_f32_e32 v105, v105
	v_mul_f32_e32 v12, v85, v12
	v_mul_f32_e32 v13, v85, v13
	v_mul_f32_e32 v14, v85, v14
	v_mul_f32_e32 v15, v85, v15
	v_mul_f32_e32 v102, v102, v174
	v_mul_f32_e32 v103, v103, v175
	v_mul_f32_e32 v104, v104, v176
	v_mul_f32_e32 v105, v105, v177
	v_exp_f32_e32 v12, v12
	v_exp_f32_e32 v13, v13
	v_exp_f32_e32 v14, v14
	v_exp_f32_e32 v15, v15
	s_nop 0
	v_fma_f32 v138, -v12, v12, 1.0 clamp
	v_fma_f32 v139, -v13, v13, 1.0 clamp
	v_fma_f32 v140, -v14, v14, 1.0 clamp
	v_fma_f32 v141, -v15, v15, 1.0 clamp
	v_sqrt_f32_e32 v138, v138
	v_sqrt_f32_e32 v139, v139
	v_sqrt_f32_e32 v140, v140
	v_sqrt_f32_e32 v141, v141
	s_nop 0
	v_mul_f32_e32 v102, v138, v102
	v_mul_f32_e32 v103, v139, v103
	v_mul_f32_e32 v104, v140, v104
	v_mul_f32_e32 v105, v141, v105
	v_add_f32_e32 v16, v16, v75
	v_add_f32_e32 v17, v17, v75
	v_add_f32_e32 v18, v18, v75
	v_add_f32_e32 v19, v19, v75
	v_add_f32_e32 v106, v106, v84
	v_add_f32_e32 v107, v107, v84
	v_add_f32_e32 v108, v108, v84
	v_add_f32_e32 v109, v109, v84
	v_exp_f32_e32 v16, v16
	v_exp_f32_e32 v17, v17
	v_exp_f32_e32 v18, v18
	v_exp_f32_e32 v19, v19
	v_exp_f32_e32 v106, v106
	v_exp_f32_e32 v107, v107
	v_exp_f32_e32 v108, v108
	v_exp_f32_e32 v109, v109
	v_add_f32_e32 v16, 1.0, v16
	v_add_f32_e32 v17, 1.0, v17
	v_add_f32_e32 v18, 1.0, v18
	v_add_f32_e32 v19, 1.0, v19
	v_add_f32_e32 v106, 1.0, v106
	v_add_f32_e32 v107, 1.0, v107
	v_add_f32_e32 v108, 1.0, v108
	v_add_f32_e32 v109, 1.0, v109
	v_rcp_f32_e32 v16, v16
	v_rcp_f32_e32 v17, v17
	v_rcp_f32_e32 v18, v18
	v_rcp_f32_e32 v19, v19
	v_rcp_f32_e32 v106, v106
	v_rcp_f32_e32 v107, v107
	v_rcp_f32_e32 v108, v108
	v_rcp_f32_e32 v109, v109
	v_mul_f32_e32 v16, v85, v16
	v_mul_f32_e32 v17, v85, v17
	v_mul_f32_e32 v18, v85, v18
	v_mul_f32_e32 v19, v85, v19
	v_mul_f32_e32 v106, v106, v178
	v_mul_f32_e32 v107, v107, v179
	v_mul_f32_e32 v108, v108, v180
	v_mul_f32_e32 v109, v109, v181
	v_exp_f32_e32 v16, v16
	v_exp_f32_e32 v17, v17
	v_exp_f32_e32 v18, v18
	v_exp_f32_e32 v19, v19
	s_nop 0
	v_fma_f32 v138, -v16, v16, 1.0 clamp
	v_fma_f32 v139, -v17, v17, 1.0 clamp
	v_fma_f32 v140, -v18, v18, 1.0 clamp
	v_fma_f32 v141, -v19, v19, 1.0 clamp
	v_sqrt_f32_e32 v138, v138
	v_sqrt_f32_e32 v139, v139
	v_sqrt_f32_e32 v140, v140
	v_sqrt_f32_e32 v141, v141
	s_nop 0
	v_mul_f32_e32 v106, v138, v106
	v_mul_f32_e32 v107, v139, v107
; __device__ __forceinline__ float bf2f(u16 h) { return __uint_as_float(((unsigned)h) << 16); }
; __device__ __forceinline__ void lru_tile(const Params& P, int chunk, int head, int pass, char* smem_raw) {
;     ...
; #pragma unroll
;       for (int tc = 0; tc < 4; ++tc)
; #pragma unroll
;         for (int reg = 0; reg < 4; ++reg) {
;           const int tl = wid * 16 + (lane >> 4) * 4 + reg;
;           const int c = 16 * tc + (lane & 15);
;           const float r = __builtin_amdgcn_rcpf(1.f + __builtin_amdgcn_exp2f(acc[tc][reg] + ba[tc]));
;           const float ii = __builtin_amdgcn_rcpf(1.f + __builtin_amdgcn_exp2f(acc[tc + 4][reg] + bi[tc]));
;           const float la = -c8[tc] * r;
;           const float a = __builtin_amdgcn_exp2f(la);
;           const float ucv = bf2f(sm_uc[(sb * 64 + tl) * LDSS + c]);
;           const float bt = __builtin_amdgcn_sqrtf(fmaxf(1.f - a * a, 0.f)) * (ii * ucv);
;           sm_a[tl * 64 + c] = a;
;           sm_b[tl * 64 + c] = bt;
;         }
;       __syncthreads();
;       const int pos = (d == 0) ? q : 3 - q;
;       {
;         float Pp = 1.f, H = 0.f;
; #pragma unroll 4
;         for (int i = 0; i < 16; ++i) {
;           const int tl = (d == 0) ? (q * 16 + i) : (q * 16 + 15 - i);
;           const float a = sm_a[tl * 64 + ch], b = sm_b[tl * 64 + ch];
;           H = a * H + b; Pp *= a;
;         }
	v_mul_f32_e32 v108, v140, v108
	v_mul_f32_e32 v109, v141, v109
	v_add_f32_e32 v20, v20, v75
	v_add_f32_e32 v21, v21, v75
	v_add_f32_e32 v22, v22, v75
	v_add_f32_e32 v23, v23, v75
	v_add_f32_e32 v110, v110, v84
	v_add_f32_e32 v111, v111, v84
	v_add_f32_e32 v112, v112, v84
	v_add_f32_e32 v113, v113, v84
	v_exp_f32_e32 v20, v20
	v_exp_f32_e32 v21, v21
	v_exp_f32_e32 v22, v22
	v_exp_f32_e32 v23, v23
	v_exp_f32_e32 v110, v110
	v_exp_f32_e32 v111, v111
	v_exp_f32_e32 v112, v112
	v_exp_f32_e32 v113, v113
	v_add_f32_e32 v20, 1.0, v20
	v_add_f32_e32 v21, 1.0, v21
	v_add_f32_e32 v22, 1.0, v22
	v_add_f32_e32 v23, 1.0, v23
	v_add_f32_e32 v110, 1.0, v110
	v_add_f32_e32 v111, 1.0, v111
	v_add_f32_e32 v112, 1.0, v112
	v_add_f32_e32 v113, 1.0, v113
	v_rcp_f32_e32 v20, v20
	v_rcp_f32_e32 v21, v21
	v_rcp_f32_e32 v22, v22
	v_rcp_f32_e32 v23, v23
	v_rcp_f32_e32 v110, v110
	v_rcp_f32_e32 v111, v111
	v_rcp_f32_e32 v112, v112
	v_rcp_f32_e32 v113, v113
	v_mul_f32_e32 v20, v85, v20
	v_mul_f32_e32 v21, v85, v21
	v_mul_f32_e32 v22, v85, v22
	v_mul_f32_e32 v23, v85, v23
	v_mul_f32_e32 v110, v110, v182
	v_mul_f32_e32 v111, v111, v183
	v_mul_f32_e32 v112, v112, v184
	v_mul_f32_e32 v113, v113, v185
	v_exp_f32_e32 v20, v20
	v_exp_f32_e32 v21, v21
	v_exp_f32_e32 v22, v22
	v_exp_f32_e32 v23, v23
	s_nop 0
	v_fma_f32 v138, -v20, v20, 1.0 clamp
	v_fma_f32 v139, -v21, v21, 1.0 clamp
	v_fma_f32 v140, -v22, v22, 1.0 clamp
	v_fma_f32 v141, -v23, v23, 1.0 clamp
	v_sqrt_f32_e32 v138, v138
	v_sqrt_f32_e32 v139, v139
	v_sqrt_f32_e32 v140, v140
	v_sqrt_f32_e32 v141, v141
	s_nop 0
	v_mul_f32_e32 v110, v138, v110
	v_mul_f32_e32 v111, v139, v111
	v_mul_f32_e32 v112, v140, v112
	v_mul_f32_e32 v113, v141, v113
	v_add_f32_e32 v24, v24, v75
	v_add_f32_e32 v25, v25, v75
	v_add_f32_e32 v26, v26, v75
	v_add_f32_e32 v27, v27, v75
	v_add_f32_e32 v114, v114, v84
	v_add_f32_e32 v115, v115, v84
	v_add_f32_e32 v116, v116, v84
	v_add_f32_e32 v117, v117, v84
	v_exp_f32_e32 v24, v24
	v_exp_f32_e32 v25, v25
	v_exp_f32_e32 v26, v26
	v_exp_f32_e32 v27, v27
	v_exp_f32_e32 v114, v114
	v_exp_f32_e32 v115, v115
	v_exp_f32_e32 v116, v116
	v_exp_f32_e32 v117, v117
	v_add_f32_e32 v24, 1.0, v24
	v_add_f32_e32 v25, 1.0, v25
	v_add_f32_e32 v26, 1.0, v26
	v_add_f32_e32 v27, 1.0, v27
	v_add_f32_e32 v114, 1.0, v114
	v_add_f32_e32 v115, 1.0, v115
	v_add_f32_e32 v116, 1.0, v116
	v_add_f32_e32 v117, 1.0, v117
	v_rcp_f32_e32 v24, v24
	v_rcp_f32_e32 v25, v25
	v_rcp_f32_e32 v26, v26
	v_rcp_f32_e32 v27, v27
	v_rcp_f32_e32 v114, v114
	v_rcp_f32_e32 v115, v115
	v_rcp_f32_e32 v116, v116
	v_rcp_f32_e32 v117, v117
	v_mul_f32_e32 v24, v85, v24
	v_mul_f32_e32 v25, v85, v25
	v_mul_f32_e32 v26, v85, v26
	v_mul_f32_e32 v27, v85, v27
	v_mul_f32_e32 v114, v114, v186
	v_mul_f32_e32 v115, v115, v187
	v_mul_f32_e32 v116, v116, v188
	v_mul_f32_e32 v117, v117, v189
	v_exp_f32_e32 v24, v24
	v_exp_f32_e32 v25, v25
	v_exp_f32_e32 v26, v26
	v_exp_f32_e32 v27, v27
	s_nop 0
	v_fma_f32 v138, -v24, v24, 1.0 clamp
	v_fma_f32 v139, -v25, v25, 1.0 clamp
	v_fma_f32 v140, -v26, v26, 1.0 clamp
	v_fma_f32 v141, -v27, v27, 1.0 clamp
	v_sqrt_f32_e32 v138, v138
	v_sqrt_f32_e32 v139, v139
	v_sqrt_f32_e32 v140, v140
	v_sqrt_f32_e32 v141, v141
	s_nop 0
	v_mul_f32_e32 v114, v138, v114
	v_mul_f32_e32 v115, v139, v115
	v_mul_f32_e32 v116, v140, v116
	v_mul_f32_e32 v117, v141, v117
	v_add_f32_e32 v28, v28, v75
	v_add_f32_e32 v29, v29, v75
	v_add_f32_e32 v30, v30, v75
	v_add_f32_e32 v31, v31, v75
	v_add_f32_e32 v118, v118, v84
	v_add_f32_e32 v119, v119, v84
	v_add_f32_e32 v120, v120, v84
	v_add_f32_e32 v121, v121, v84
	v_exp_f32_e32 v28, v28
	v_exp_f32_e32 v29, v29
	v_exp_f32_e32 v30, v30
	v_exp_f32_e32 v31, v31
	v_exp_f32_e32 v118, v118
	v_exp_f32_e32 v119, v119
	v_exp_f32_e32 v120, v120
	v_exp_f32_e32 v121, v121
	v_add_f32_e32 v28, 1.0, v28
	v_add_f32_e32 v29, 1.0, v29
	v_add_f32_e32 v30, 1.0, v30
	v_add_f32_e32 v31, 1.0, v31
	v_add_f32_e32 v118, 1.0, v118
	v_add_f32_e32 v119, 1.0, v119
	v_add_f32_e32 v120, 1.0, v120
	v_add_f32_e32 v121, 1.0, v121
	v_rcp_f32_e32 v28, v28
	v_rcp_f32_e32 v29, v29
	v_rcp_f32_e32 v30, v30
	v_rcp_f32_e32 v31, v31
	v_rcp_f32_e32 v118, v118
	v_rcp_f32_e32 v119, v119
	v_rcp_f32_e32 v120, v120
	v_rcp_f32_e32 v121, v121
	v_mul_f32_e32 v28, v85, v28
	v_mul_f32_e32 v29, v85, v29
	v_mul_f32_e32 v30, v85, v30
	v_mul_f32_e32 v31, v85, v31
	v_mul_f32_e32 v118, v118, v190
	v_mul_f32_e32 v119, v119, v191
	v_mul_f32_e32 v120, v120, v192
	v_mul_f32_e32 v121, v121, v193
	v_exp_f32_e32 v28, v28
	v_exp_f32_e32 v29, v29
	v_exp_f32_e32 v30, v30
	v_exp_f32_e32 v31, v31
	s_nop 0
	v_fma_f32 v138, -v28, v28, 1.0 clamp
	v_fma_f32 v139, -v29, v29, 1.0 clamp
	v_fma_f32 v140, -v30, v30, 1.0 clamp
	v_fma_f32 v141, -v31, v31, 1.0 clamp
	v_sqrt_f32_e32 v138, v138
	v_sqrt_f32_e32 v139, v139
	v_sqrt_f32_e32 v140, v140
	v_sqrt_f32_e32 v141, v141
	s_nop 0
	v_mul_f32_e32 v118, v138, v118
	v_mul_f32_e32 v119, v139, v119
	v_mul_f32_e32 v120, v140, v120
	v_mul_f32_e32 v121, v141, v121
	v_mov_b32_e32 v253, v0
	v_mov_b32_e32 v254, v90
	v_fma_f32 v254, v1, v254, v91
	v_mul_f32_e32 v253, v253, v1
	v_fma_f32 v254, v2, v254, v92
	v_mul_f32_e32 v253, v253, v2
	v_fma_f32 v254, v3, v254, v93
	v_mul_f32_e32 v253, v253, v3
	v_fma_f32 v254, v4, v254, v94
	v_mul_f32_e32 v253, v253, v4
	v_fma_f32 v254, v5, v254, v95
	v_mul_f32_e32 v253, v253, v5
	v_fma_f32 v254, v6, v254, v96
	v_mul_f32_e32 v253, v253, v6
	v_fma_f32 v254, v7, v254, v97
	v_mul_f32_e32 v253, v253, v7
	v_fma_f32 v254, v8, v254, v98
	v_mul_f32_e32 v253, v253, v8
	v_fma_f32 v254, v9, v254, v99
	v_mul_f32_e32 v253, v253, v9
	v_fma_f32 v254, v10, v254, v100
	v_mul_f32_e32 v253, v253, v10
	v_fma_f32 v254, v11, v254, v101
; __device__ __forceinline__ float bf2f(u16 h) { return __uint_as_float(((unsigned)h) << 16); }
; __device__ __forceinline__ void lru_tile(const Params& P, int chunk, int head, int pass, char* smem_raw) {
;     ...
;         const bf16x8 af = *reinterpret_cast<const bf16x8*>(&sm_uc[(sb * 64 + wid * 16 + (lane & 15)) * LDSS + s * 32 + (lane >> 4) * 8]);
; #pragma unroll
;         for (int t = 0; t < 8; ++t) {
;           const bf16x8 bfr = *reinterpret_cast<const bf16x8*>(&sm_w[(t * 16 + (lane & 15)) * LDSS + s * 32 + (lane >> 4) * 8]);
;           acc[t] = __builtin_amdgcn_mfma_f32_16x16x32_bf16(af, bfr, acc[t], 0, 0, 0);
;         }
;       }
;     ...
;       const float2 p0 = sm_ph[ch], p1 = sm_ph[64 + ch], p2 = sm_ph[128 + ch], p3 = sm_ph[192 + ch];
;       if (pass == 2) {
;         float hin = cB;
;         if (pos > 0) hin = p0.x * hin + p0.y;
;         if (pos > 1) hin = p1.x * hin + p1.y;
;         if (pos > 2) hin = p2.x * hin + p2.y;
;         float h = hin;
;         float hfp[16], gp[16];
;         if (d == 1) {
; #pragma unroll
;           for (int i = 0; i < 16; ++i) {
;             const long rowp = row0 + sb * 64 + q * 16 + 15 - i;
;             hfp[i] = hfbuf[rowp * 512 + gch];
;             gp[i] = bf2f(P.zq[rowp * 1536 + 512 + gch]);
;           }
;         }
; #pragma unroll
;         for (int i = 0; i < 16; ++i) {
;           const int tl = (d == 0) ? (q * 16 + i) : (q * 16 + 15 - i);
;           const float a = sm_a[tl * 64 + ch], b = sm_b[tl * 64 + ch];
;           h = a * h + b;
;           const long row = row0 + sb * 64 + tl;
;           if (d == 0) {
;             hfw[row * 512 + gch] = h;
	v_mul_f32_e32 v253, v253, v11
	v_fma_f32 v254, v12, v254, v102
	v_mul_f32_e32 v253, v253, v12
	v_fma_f32 v254, v13, v254, v103
	v_mul_f32_e32 v253, v253, v13
	v_fma_f32 v254, v14, v254, v104
	v_mul_f32_e32 v253, v253, v14
	v_fma_f32 v254, v15, v254, v105
	v_mul_f32_e32 v253, v253, v15
	v_fma_f32 v254, v16, v254, v106
	v_mul_f32_e32 v253, v253, v16
	v_fma_f32 v254, v17, v254, v107
	v_mul_f32_e32 v253, v253, v17
	v_fma_f32 v254, v18, v254, v108
	v_mul_f32_e32 v253, v253, v18
	v_fma_f32 v254, v19, v254, v109
	v_mul_f32_e32 v253, v253, v19
	v_fma_f32 v254, v20, v254, v110
	v_mul_f32_e32 v253, v253, v20
	v_fma_f32 v254, v21, v254, v111
	v_mul_f32_e32 v253, v253, v21
	v_fma_f32 v254, v22, v254, v112
	v_mul_f32_e32 v253, v253, v22
	v_fma_f32 v254, v23, v254, v113
	v_mul_f32_e32 v253, v253, v23
	v_fma_f32 v254, v24, v254, v114
	v_mul_f32_e32 v253, v253, v24
	v_fma_f32 v254, v25, v254, v115
	v_mul_f32_e32 v253, v253, v25
	v_fma_f32 v254, v26, v254, v116
	v_mul_f32_e32 v253, v253, v26
	v_fma_f32 v254, v27, v254, v117
	v_mul_f32_e32 v253, v253, v27
	v_fma_f32 v254, v28, v254, v118
	v_mul_f32_e32 v253, v253, v28
	v_fma_f32 v254, v29, v254, v119
	v_mul_f32_e32 v253, v253, v29
	v_fma_f32 v254, v30, v254, v120
	v_mul_f32_e32 v253, v253, v30
	v_fma_f32 v254, v31, v254, v121
	v_mul_f32_e32 v253, v253, v31
	v_mov_b32_e32 v138, v253
	v_mov_b32_e32 v139, v253
	s_nop 1
	v_permlane16_swap_b32_e32 v138, v139
	v_mov_b32_e32 v140, v138
	v_mov_b32_e32 v141, v139
	s_nop 1
	v_permlane32_swap_b32_e32 v138, v140
	v_permlane32_swap_b32_e32 v139, v141
	v_mov_b32_e32 v198, v254
	v_mov_b32_e32 v199, v254
	s_nop 1
	v_permlane16_swap_b32_e32 v198, v199
	v_mov_b32_e32 v200, v198
	v_mov_b32_e32 v201, v199
	s_nop 1
	v_permlane32_swap_b32_e32 v198, v200
	v_permlane32_swap_b32_e32 v199, v201
	v_mov_b32_e32 v136, v148
	v_fma_f32 v150, v138, v136, v198
	v_fma_f32 v151, v139, v150, v199
	v_fma_f32 v202, v140, v151, v200
	v_mov_b32_e32 v254, v136
	v_cndmask_b32_e64 v254, v254, v150, s[72:73]
	v_cndmask_b32_e64 v254, v254, v151, s[74:75]
	v_cndmask_b32_e64 v254, v254, v202, s[76:77]
	v_fma_f32 v205, v0, v254, v90
	v_fma_f32 v206, v1, v205, v91
	v_fma_f32 v207, v2, v206, v92
	v_fma_f32 v208, v3, v207, v93
	v_fma_f32 v209, v4, v208, v94
	v_fma_f32 v210, v5, v209, v95
	v_fma_f32 v211, v6, v210, v96
	v_fma_f32 v212, v7, v211, v97
	v_fma_f32 v213, v8, v212, v98
	v_fma_f32 v214, v9, v213, v99
	v_fma_f32 v215, v10, v214, v100
	v_fma_f32 v216, v11, v215, v101
	v_fma_f32 v217, v12, v216, v102
	v_fma_f32 v218, v13, v217, v103
	v_fma_f32 v219, v14, v218, v104
	v_fma_f32 v220, v15, v219, v105
	v_fma_f32 v221, v16, v220, v106
	v_fma_f32 v222, v17, v221, v107
	v_fma_f32 v223, v18, v222, v108
	v_fma_f32 v224, v19, v223, v109
	v_fma_f32 v225, v20, v224, v110
	v_fma_f32 v226, v21, v225, v111
	v_fma_f32 v227, v22, v226, v112
	v_fma_f32 v228, v23, v227, v113
	v_fma_f32 v229, v24, v228, v114
	v_fma_f32 v230, v25, v229, v115
	v_fma_f32 v231, v26, v230, v116
	v_fma_f32 v232, v27, v231, v117
	v_fma_f32 v233, v28, v232, v118
	v_fma_f32 v234, v29, v233, v119
	v_fma_f32 v235, v30, v234, v120
	v_fma_f32 v236, v31, v235, v121
	ds_read_b128 v[76:79], v131 offset:0
	ds_read_b128 v[80:83], v133 offset:0
	ds_read_b128 v[122:125], v131 offset:512
	ds_read_b128 v[126:129], v133 offset:512
	s_waitcnt vmcnt(0)
	s_waitcnt lgkmcnt(3)
	v_mfma_f32_16x16x32_bf16 v[0:3], v[76:79], v[238:241], 0
	v_mfma_f32_16x16x32_bf16 v[90:93], v[76:79], v[246:249], 0
	ds_read_b128 v[76:79], v131 offset:1024
	s_waitcnt lgkmcnt(3)
	v_mfma_f32_16x16x32_bf16 v[0:3], v[80:83], v[242:245], v[0:3]
	v_mfma_f32_16x16x32_bf16 v[90:93], v[80:83], v[194:197], v[90:93]
	ds_read_b128 v[80:83], v133 offset:1024
	s_waitcnt lgkmcnt(3)
	v_mfma_f32_16x16x32_bf16 v[4:7], v[122:125], v[238:241], 0
	v_mfma_f32_16x16x32_bf16 v[94:97], v[122:125], v[246:249], 0
	ds_read_b128 v[122:125], v131 offset:1536
	s_waitcnt lgkmcnt(3)
	v_mfma_f32_16x16x32_bf16 v[4:7], v[126:129], v[242:245], v[4:7]
	v_mfma_f32_16x16x32_bf16 v[94:97], v[126:129], v[194:197], v[94:97]
	ds_read_b128 v[126:129], v133 offset:1536
	s_waitcnt lgkmcnt(3)
	v_mfma_f32_16x16x32_bf16 v[8:11], v[76:79], v[238:241], 0
	v_mfma_f32_16x16x32_bf16 v[98:101], v[76:79], v[246:249], 0
	ds_read_b128 v[76:79], v131 offset:2048
	s_waitcnt lgkmcnt(3)
	v_mfma_f32_16x16x32_bf16 v[8:11], v[80:83], v[242:245], v[8:11]
	v_mfma_f32_16x16x32_bf16 v[98:101], v[80:83], v[194:197], v[98:101]
	ds_read_b128 v[80:83], v133 offset:2048
	s_waitcnt lgkmcnt(3)
	v_mfma_f32_16x16x32_bf16 v[12:15], v[122:125], v[238:241], 0
	v_mfma_f32_16x16x32_bf16 v[102:105], v[122:125], v[246:249], 0
	ds_read_b128 v[122:125], v131 offset:2560
	s_waitcnt lgkmcnt(3)
	v_mfma_f32_16x16x32_bf16 v[12:15], v[126:129], v[242:245], v[12:15]
	v_mfma_f32_16x16x32_bf16 v[102:105], v[126:129], v[194:197], v[102:105]
	ds_read_b128 v[126:129], v133 offset:2560
	s_waitcnt lgkmcnt(3)
	v_mfma_f32_16x16x32_bf16 v[16:19], v[76:79], v[238:241], 0
	v_mfma_f32_16x16x32_bf16 v[106:109], v[76:79], v[246:249], 0
	ds_read_b128 v[76:79], v131 offset:3072
	s_waitcnt lgkmcnt(3)
	v_mfma_f32_16x16x32_bf16 v[16:19], v[80:83], v[242:245], v[16:19]
	v_mfma_f32_16x16x32_bf16 v[106:109], v[80:83], v[194:197], v[106:109]
	ds_read_b128 v[80:83], v133 offset:3072
	s_waitcnt lgkmcnt(3)
	v_mfma_f32_16x16x32_bf16 v[20:23], v[122:125], v[238:241], 0
	v_mfma_f32_16x16x32_bf16 v[110:113], v[122:125], v[246:249], 0
	ds_read_b128 v[122:125], v131 offset:3584
	s_waitcnt lgkmcnt(3)
	v_mfma_f32_16x16x32_bf16 v[20:23], v[126:129], v[242:245], v[20:23]
	v_mfma_f32_16x16x32_bf16 v[110:113], v[126:129], v[194:197], v[110:113]
	ds_read_b128 v[126:129], v133 offset:3584
	s_waitcnt lgkmcnt(3)
; __device__ __forceinline__ void lru_tile(const Params& P, int chunk, int head, int pass, char* smem_raw) {
;     ...
;       *reinterpret_cast<uint4*>(&sm_w[rowi * LDSS + kg * 8]) = ldg16(P.wg + ((long)(d * 8 + head) * 128 + rowi) * 64 + kg * 8);
;     }
;     float ba[4], bi[4], c8[4];
; #pragma unroll
;     for (int tc = 0; tc < 4; ++tc) {
;       const int cidx = d * 512 + head * 64 + 16 * tc + (lane & 15);
;       ba[tc] = P.b_a[cidx] * -1.4426950408889634f; bi[tc] = P.b_i[cidx] * -1.4426950408889634f;
;       const float nl = -P.lam[cidx];
;       const float e_ = __expf(nl);
;       const float sp = (nl > 20.f) ? nl
;                      : (e_ < 0.03f ? e_ * (1.f - e_ * (0.5f - e_ * (0.33333334f - 0.25f * e_))) : __logf(1.f + e_));
;       c8[tc] = 8.f * 1.4426950408889634f * sp;
;     }
;     __syncthreads();
;     float cA = 1.f, cB = (pass == 2) ? sm_init[d * 64 + ch] : 0.f;
;     for (int sbi = 0; sbi < 2; ++sbi) {
;       const int sb = (d == 0) ? sbi : 1 - sbi;
;       f32x4 acc[8];
; #pragma unroll
;       for (int t = 0; t < 8; ++t) acc[t] = f32x4{0.f, 0.f, 0.f, 0.f};
; #pragma unroll
;       for (int s = 0; s < 2; ++s) {
;         const bf16x8 af = *reinterpret_cast<const bf16x8*>(&sm_uc[(sb * 64 + wid * 16 + (lane & 15)) * LDSS + s * 32 + (lane >> 4) * 8]);
; #pragma unroll
;         for (int t = 0; t < 8; ++t) {
;           const bf16x8 bfr = *reinterpret_cast<const bf16x8*>(&sm_w[(t * 16 + (lane & 15)) * LDSS + s * 32 + (lane >> 4) * 8]);
;           acc[t] = __builtin_amdgcn_mfma_f32_16x16x32_bf16(af, bfr, acc[t], 0, 0, 0);
;         }
;       }
; #pragma unroll
;       for (int tc = 0; tc < 4; ++tc)
; #pragma unroll
;         for (int reg = 0; reg < 4; ++reg) {
;           const int tl = wid * 16 + (lane >> 4) * 4 + reg;
;           const int c = 16 * tc + (lane & 15);
;           const float r = __builtin_amdgcn_rcpf(1.f + __builtin_amdgcn_exp2f(acc[tc][reg] + ba[tc]));
;           const float ii = __builtin_amdgcn_rcpf(1.f + __builtin_amdgcn_exp2f(acc[tc + 4][reg] + bi[tc]));
;           const float la = -c8[tc] * r;
;           const float a = __builtin_amdgcn_exp2f(la);
;           const float ucv = bf2f(sm_uc[(sb * 64 + tl) * LDSS + c]);
;           const float bt = __builtin_amdgcn_sqrtf(fmaxf(1.f - a * a, 0.f)) * (ii * ucv);
;           sm_a[tl * 64 + c] = a;
;           sm_b[tl * 64 + c] = bt;
;         }
	v_mfma_f32_16x16x32_bf16 v[24:27], v[76:79], v[238:241], 0
	v_mfma_f32_16x16x32_bf16 v[114:117], v[76:79], v[246:249], 0
	s_waitcnt lgkmcnt(2)
	v_mfma_f32_16x16x32_bf16 v[24:27], v[80:83], v[242:245], v[24:27]
	v_mfma_f32_16x16x32_bf16 v[114:117], v[80:83], v[194:197], v[114:117]
	s_waitcnt lgkmcnt(1)
	v_mfma_f32_16x16x32_bf16 v[28:31], v[122:125], v[238:241], 0
	v_mfma_f32_16x16x32_bf16 v[118:121], v[122:125], v[246:249], 0
	s_waitcnt lgkmcnt(0)
	v_mfma_f32_16x16x32_bf16 v[28:31], v[126:129], v[242:245], v[28:31]
	v_mfma_f32_16x16x32_bf16 v[118:121], v[126:129], v[194:197], v[118:121]
	s_lshl_b32 s0, s56, 8
	s_add_u32 s0, s0, 0x0
	s_add_u32 s4, s20, s0
	s_addc_u32 s5, s21, 0
	global_load_dwordx4 v[238:241], v251, s[4:5]
	global_load_dwordx4 v[242:245], v251, s[4:5] offset:64
	s_add_u32 s4, s4, 0x2000
	s_addc_u32 s5, s5, 0
	global_load_dwordx4 v[246:249], v251, s[4:5]
	global_load_dwordx4 v[194:197], v251, s[4:5] offset:64
	s_nop 7
	s_nop 7
	v_add_f32_e32 v0, v0, v145
	v_add_f32_e32 v1, v1, v145
	v_add_f32_e32 v2, v2, v145
	v_add_f32_e32 v3, v3, v145
	v_add_f32_e32 v90, v90, v146
	v_add_f32_e32 v91, v91, v146
	v_add_f32_e32 v92, v92, v146
	v_add_f32_e32 v93, v93, v146
	v_exp_f32_e32 v0, v0
	v_exp_f32_e32 v1, v1
	v_exp_f32_e32 v2, v2
	v_exp_f32_e32 v3, v3
	v_exp_f32_e32 v90, v90
	v_exp_f32_e32 v91, v91
	v_exp_f32_e32 v92, v92
	v_exp_f32_e32 v93, v93
	v_add_f32_e32 v0, 1.0, v0
	v_add_f32_e32 v1, 1.0, v1
	v_add_f32_e32 v2, 1.0, v2
	v_add_f32_e32 v3, 1.0, v3
	v_add_f32_e32 v90, 1.0, v90
	v_add_f32_e32 v91, 1.0, v91
	v_add_f32_e32 v92, 1.0, v92
	v_add_f32_e32 v93, 1.0, v93
	v_rcp_f32_e32 v0, v0
	v_rcp_f32_e32 v1, v1
	v_rcp_f32_e32 v2, v2
	v_rcp_f32_e32 v3, v3
	v_rcp_f32_e32 v90, v90
	v_rcp_f32_e32 v91, v91
	v_rcp_f32_e32 v92, v92
	v_rcp_f32_e32 v93, v93
	v_mul_f32_e32 v0, v147, v0
	v_mul_f32_e32 v1, v147, v1
	v_mul_f32_e32 v2, v147, v2
	v_mul_f32_e32 v3, v147, v3
	v_mul_f32_e32 v90, v90, v162
	v_mul_f32_e32 v91, v91, v163
	v_mul_f32_e32 v92, v92, v164
	v_mul_f32_e32 v93, v93, v165
	v_exp_f32_e32 v0, v0
	v_exp_f32_e32 v1, v1
	v_exp_f32_e32 v2, v2
	v_exp_f32_e32 v3, v3
	s_nop 0
	v_fma_f32 v138, -v0, v0, 1.0 clamp
	v_fma_f32 v139, -v1, v1, 1.0 clamp
	v_fma_f32 v140, -v2, v2, 1.0 clamp
	v_fma_f32 v141, -v3, v3, 1.0 clamp
	v_sqrt_f32_e32 v138, v138
	v_sqrt_f32_e32 v139, v139
	v_sqrt_f32_e32 v140, v140
	v_sqrt_f32_e32 v141, v141
	s_nop 0
	v_mul_f32_e32 v90, v138, v90
	v_mul_f32_e32 v91, v139, v91
	v_mul_f32_e32 v92, v140, v92
	v_mul_f32_e32 v93, v141, v93
	v_add_f32_e32 v4, v4, v145
	v_add_f32_e32 v5, v5, v145
	v_add_f32_e32 v6, v6, v145
	v_add_f32_e32 v7, v7, v145
	v_add_f32_e32 v94, v94, v146
	v_add_f32_e32 v95, v95, v146
	v_add_f32_e32 v96, v96, v146
	v_add_f32_e32 v97, v97, v146
	v_exp_f32_e32 v4, v4
	v_exp_f32_e32 v5, v5
	v_exp_f32_e32 v6, v6
	v_exp_f32_e32 v7, v7
	v_exp_f32_e32 v94, v94
	v_exp_f32_e32 v95, v95
	v_exp_f32_e32 v96, v96
	v_exp_f32_e32 v97, v97
	v_add_f32_e32 v4, 1.0, v4
	v_add_f32_e32 v5, 1.0, v5
	v_add_f32_e32 v6, 1.0, v6
	v_add_f32_e32 v7, 1.0, v7
	v_add_f32_e32 v94, 1.0, v94
	v_add_f32_e32 v95, 1.0, v95
	v_add_f32_e32 v96, 1.0, v96
	v_add_f32_e32 v97, 1.0, v97
	v_rcp_f32_e32 v4, v4
	v_rcp_f32_e32 v5, v5
	v_rcp_f32_e32 v6, v6
	v_rcp_f32_e32 v7, v7
	v_rcp_f32_e32 v94, v94
	v_rcp_f32_e32 v95, v95
	v_rcp_f32_e32 v96, v96
	v_rcp_f32_e32 v97, v97
	v_mul_f32_e32 v4, v147, v4
	v_mul_f32_e32 v5, v147, v5
	v_mul_f32_e32 v6, v147, v6
	v_mul_f32_e32 v7, v147, v7
	v_mul_f32_e32 v94, v94, v166
	v_mul_f32_e32 v95, v95, v167
	v_mul_f32_e32 v96, v96, v168
	v_mul_f32_e32 v97, v97, v169
	v_exp_f32_e32 v4, v4
	v_exp_f32_e32 v5, v5
	v_exp_f32_e32 v6, v6
	v_exp_f32_e32 v7, v7
	s_nop 0
	v_fma_f32 v138, -v4, v4, 1.0 clamp
	v_fma_f32 v139, -v5, v5, 1.0 clamp
	v_fma_f32 v140, -v6, v6, 1.0 clamp
	v_fma_f32 v141, -v7, v7, 1.0 clamp
	v_sqrt_f32_e32 v138, v138
	v_sqrt_f32_e32 v139, v139
	v_sqrt_f32_e32 v140, v140
	v_sqrt_f32_e32 v141, v141
	s_nop 0
	v_mul_f32_e32 v94, v138, v94
	v_mul_f32_e32 v95, v139, v95
	v_mul_f32_e32 v96, v140, v96
	v_mul_f32_e32 v97, v141, v97
	v_add_f32_e32 v8, v8, v145
	v_add_f32_e32 v9, v9, v145
	v_add_f32_e32 v10, v10, v145
	v_add_f32_e32 v11, v11, v145
	v_add_f32_e32 v98, v98, v146
	v_add_f32_e32 v99, v99, v146
	v_add_f32_e32 v100, v100, v146
	v_add_f32_e32 v101, v101, v146
	v_exp_f32_e32 v8, v8
	v_exp_f32_e32 v9, v9
	v_exp_f32_e32 v10, v10
	v_exp_f32_e32 v11, v11
	v_exp_f32_e32 v98, v98
	v_exp_f32_e32 v99, v99
	v_exp_f32_e32 v100, v100
	v_exp_f32_e32 v101, v101
	v_add_f32_e32 v8, 1.0, v8
	v_add_f32_e32 v9, 1.0, v9
	v_add_f32_e32 v10, 1.0, v10
	v_add_f32_e32 v11, 1.0, v11
	v_add_f32_e32 v98, 1.0, v98
	v_add_f32_e32 v99, 1.0, v99
	v_add_f32_e32 v100, 1.0, v100
	v_add_f32_e32 v101, 1.0, v101
	v_rcp_f32_e32 v8, v8
	v_rcp_f32_e32 v9, v9
	v_rcp_f32_e32 v10, v10
	v_rcp_f32_e32 v11, v11
	v_rcp_f32_e32 v98, v98
	v_rcp_f32_e32 v99, v99
	v_rcp_f32_e32 v100, v100
	v_rcp_f32_e32 v101, v101
	v_mul_f32_e32 v8, v147, v8
	v_mul_f32_e32 v9, v147, v9
	v_mul_f32_e32 v10, v147, v10
	v_mul_f32_e32 v11, v147, v11
	v_mul_f32_e32 v98, v98, v170
	v_mul_f32_e32 v99, v99, v171
	v_mul_f32_e32 v100, v100, v172
	v_mul_f32_e32 v101, v101, v173
	v_exp_f32_e32 v8, v8
	v_exp_f32_e32 v9, v9
	v_exp_f32_e32 v10, v10
	v_exp_f32_e32 v11, v11
	s_nop 0
	v_fma_f32 v138, -v8, v8, 1.0 clamp
	v_fma_f32 v139, -v9, v9, 1.0 clamp
	v_fma_f32 v140, -v10, v10, 1.0 clamp
	v_fma_f32 v141, -v11, v11, 1.0 clamp
	v_sqrt_f32_e32 v138, v138
	v_sqrt_f32_e32 v139, v139
	v_sqrt_f32_e32 v140, v140
	v_sqrt_f32_e32 v141, v141
	s_nop 0
	v_mul_f32_e32 v98, v138, v98
	v_mul_f32_e32 v99, v139, v99
	v_mul_f32_e32 v100, v140, v100
	v_mul_f32_e32 v101, v141, v101
	v_add_f32_e32 v12, v12, v145
; __device__ __forceinline__ float bf2f(u16 h) { return __uint_as_float(((unsigned)h) << 16); }
; __device__ __forceinline__ void lru_tile(const Params& P, int chunk, int head, int pass, char* smem_raw) {
;     ...
; #pragma unroll
;       for (int tc = 0; tc < 4; ++tc)
; #pragma unroll
;         for (int reg = 0; reg < 4; ++reg) {
;           const int tl = wid * 16 + (lane >> 4) * 4 + reg;
;           const int c = 16 * tc + (lane & 15);
;           const float r = __builtin_amdgcn_rcpf(1.f + __builtin_amdgcn_exp2f(acc[tc][reg] + ba[tc]));
;           const float ii = __builtin_amdgcn_rcpf(1.f + __builtin_amdgcn_exp2f(acc[tc + 4][reg] + bi[tc]));
;           const float la = -c8[tc] * r;
;           const float a = __builtin_amdgcn_exp2f(la);
;           const float ucv = bf2f(sm_uc[(sb * 64 + tl) * LDSS + c]);
;           const float bt = __builtin_amdgcn_sqrtf(fmaxf(1.f - a * a, 0.f)) * (ii * ucv);
;           sm_a[tl * 64 + c] = a;
;           sm_b[tl * 64 + c] = bt;
;         }
	v_add_f32_e32 v13, v13, v145
	v_add_f32_e32 v14, v14, v145
	v_add_f32_e32 v15, v15, v145
	v_add_f32_e32 v102, v102, v146
	v_add_f32_e32 v103, v103, v146
	v_add_f32_e32 v104, v104, v146
	v_add_f32_e32 v105, v105, v146
	v_exp_f32_e32 v12, v12
	v_exp_f32_e32 v13, v13
	v_exp_f32_e32 v14, v14
	v_exp_f32_e32 v15, v15
	v_exp_f32_e32 v102, v102
	v_exp_f32_e32 v103, v103
	v_exp_f32_e32 v104, v104
	v_exp_f32_e32 v105, v105
	v_add_f32_e32 v12, 1.0, v12
	v_add_f32_e32 v13, 1.0, v13
	v_add_f32_e32 v14, 1.0, v14
	v_add_f32_e32 v15, 1.0, v15
	v_add_f32_e32 v102, 1.0, v102
	v_add_f32_e32 v103, 1.0, v103
	v_add_f32_e32 v104, 1.0, v104
	v_add_f32_e32 v105, 1.0, v105
	v_rcp_f32_e32 v12, v12
	v_rcp_f32_e32 v13, v13
	v_rcp_f32_e32 v14, v14
	v_rcp_f32_e32 v15, v15
	v_rcp_f32_e32 v102, v102
	v_rcp_f32_e32 v103, v103
	v_rcp_f32_e32 v104, v104
	v_rcp_f32_e32 v105, v105
	v_mul_f32_e32 v12, v147, v12
	v_mul_f32_e32 v13, v147, v13
	v_mul_f32_e32 v14, v147, v14
	v_mul_f32_e32 v15, v147, v15
	v_mul_f32_e32 v102, v102, v174
	v_mul_f32_e32 v103, v103, v175
	v_mul_f32_e32 v104, v104, v176
	v_mul_f32_e32 v105, v105, v177
	v_exp_f32_e32 v12, v12
	v_exp_f32_e32 v13, v13
	v_exp_f32_e32 v14, v14
	v_exp_f32_e32 v15, v15
	s_nop 0
	v_fma_f32 v138, -v12, v12, 1.0 clamp
	v_fma_f32 v139, -v13, v13, 1.0 clamp
	v_fma_f32 v140, -v14, v14, 1.0 clamp
	v_fma_f32 v141, -v15, v15, 1.0 clamp
	v_sqrt_f32_e32 v138, v138
	v_sqrt_f32_e32 v139, v139
	v_sqrt_f32_e32 v140, v140
	v_sqrt_f32_e32 v141, v141
	s_nop 0
	v_mul_f32_e32 v102, v138, v102
	v_mul_f32_e32 v103, v139, v103
	v_mul_f32_e32 v104, v140, v104
	v_mul_f32_e32 v105, v141, v105
	v_add_f32_e32 v16, v16, v145
	v_add_f32_e32 v17, v17, v145
	v_add_f32_e32 v18, v18, v145
	v_add_f32_e32 v19, v19, v145
	v_add_f32_e32 v106, v106, v146
	v_add_f32_e32 v107, v107, v146
	v_add_f32_e32 v108, v108, v146
	v_add_f32_e32 v109, v109, v146
	v_exp_f32_e32 v16, v16
	v_exp_f32_e32 v17, v17
	v_exp_f32_e32 v18, v18
	v_exp_f32_e32 v19, v19
	v_exp_f32_e32 v106, v106
	v_exp_f32_e32 v107, v107
	v_exp_f32_e32 v108, v108
	v_exp_f32_e32 v109, v109
	v_add_f32_e32 v16, 1.0, v16
	v_add_f32_e32 v17, 1.0, v17
	v_add_f32_e32 v18, 1.0, v18
	v_add_f32_e32 v19, 1.0, v19
	v_add_f32_e32 v106, 1.0, v106
	v_add_f32_e32 v107, 1.0, v107
	v_add_f32_e32 v108, 1.0, v108
	v_add_f32_e32 v109, 1.0, v109
	v_rcp_f32_e32 v16, v16
	v_rcp_f32_e32 v17, v17
	v_rcp_f32_e32 v18, v18
	v_rcp_f32_e32 v19, v19
	v_rcp_f32_e32 v106, v106
	v_rcp_f32_e32 v107, v107
	v_rcp_f32_e32 v108, v108
	v_rcp_f32_e32 v109, v109
	v_mul_f32_e32 v16, v147, v16
	v_mul_f32_e32 v17, v147, v17
	v_mul_f32_e32 v18, v147, v18
	v_mul_f32_e32 v19, v147, v19
	v_mul_f32_e32 v106, v106, v178
	v_mul_f32_e32 v107, v107, v179
	v_mul_f32_e32 v108, v108, v180
	v_mul_f32_e32 v109, v109, v181
	v_exp_f32_e32 v16, v16
	v_exp_f32_e32 v17, v17
	v_exp_f32_e32 v18, v18
	v_exp_f32_e32 v19, v19
	s_nop 0
	v_fma_f32 v138, -v16, v16, 1.0 clamp
	v_fma_f32 v139, -v17, v17, 1.0 clamp
	v_fma_f32 v140, -v18, v18, 1.0 clamp
	v_fma_f32 v141, -v19, v19, 1.0 clamp
	v_sqrt_f32_e32 v138, v138
	v_sqrt_f32_e32 v139, v139
	v_sqrt_f32_e32 v140, v140
	v_sqrt_f32_e32 v141, v141
	s_nop 0
	v_mul_f32_e32 v106, v138, v106
	v_mul_f32_e32 v107, v139, v107
	v_mul_f32_e32 v108, v140, v108
	v_mul_f32_e32 v109, v141, v109
	v_add_f32_e32 v20, v20, v145
	v_add_f32_e32 v21, v21, v145
	v_add_f32_e32 v22, v22, v145
	v_add_f32_e32 v23, v23, v145
	v_add_f32_e32 v110, v110, v146
	v_add_f32_e32 v111, v111, v146
	v_add_f32_e32 v112, v112, v146
	v_add_f32_e32 v113, v113, v146
	v_exp_f32_e32 v20, v20
	v_exp_f32_e32 v21, v21
	v_exp_f32_e32 v22, v22
	v_exp_f32_e32 v23, v23
	v_exp_f32_e32 v110, v110
	v_exp_f32_e32 v111, v111
	v_exp_f32_e32 v112, v112
	v_exp_f32_e32 v113, v113
	v_add_f32_e32 v20, 1.0, v20
	v_add_f32_e32 v21, 1.0, v21
	v_add_f32_e32 v22, 1.0, v22
	v_add_f32_e32 v23, 1.0, v23
	v_add_f32_e32 v110, 1.0, v110
	v_add_f32_e32 v111, 1.0, v111
	v_add_f32_e32 v112, 1.0, v112
	v_add_f32_e32 v113, 1.0, v113
	v_rcp_f32_e32 v20, v20
	v_rcp_f32_e32 v21, v21
	v_rcp_f32_e32 v22, v22
	v_rcp_f32_e32 v23, v23
	v_rcp_f32_e32 v110, v110
	v_rcp_f32_e32 v111, v111
	v_rcp_f32_e32 v112, v112
	v_rcp_f32_e32 v113, v113
	v_mul_f32_e32 v20, v147, v20
	v_mul_f32_e32 v21, v147, v21
	v_mul_f32_e32 v22, v147, v22
	v_mul_f32_e32 v23, v147, v23
	v_mul_f32_e32 v110, v110, v182
	v_mul_f32_e32 v111, v111, v183
	v_mul_f32_e32 v112, v112, v184
	v_mul_f32_e32 v113, v113, v185
	v_exp_f32_e32 v20, v20
	v_exp_f32_e32 v21, v21
	v_exp_f32_e32 v22, v22
	v_exp_f32_e32 v23, v23
	s_nop 0
	v_fma_f32 v138, -v20, v20, 1.0 clamp
	v_fma_f32 v139, -v21, v21, 1.0 clamp
	v_fma_f32 v140, -v22, v22, 1.0 clamp
	v_fma_f32 v141, -v23, v23, 1.0 clamp
	v_sqrt_f32_e32 v138, v138
	v_sqrt_f32_e32 v139, v139
	v_sqrt_f32_e32 v140, v140
	v_sqrt_f32_e32 v141, v141
	s_nop 0
	v_mul_f32_e32 v110, v138, v110
	v_mul_f32_e32 v111, v139, v111
	v_mul_f32_e32 v112, v140, v112
	v_mul_f32_e32 v113, v141, v113
	v_add_f32_e32 v24, v24, v145
	v_add_f32_e32 v25, v25, v145
	v_add_f32_e32 v26, v26, v145
	v_add_f32_e32 v27, v27, v145
	v_add_f32_e32 v114, v114, v146
	v_add_f32_e32 v115, v115, v146
	v_add_f32_e32 v116, v116, v146
	v_add_f32_e32 v117, v117, v146
	v_exp_f32_e32 v24, v24
	v_exp_f32_e32 v25, v25
	v_exp_f32_e32 v26, v26
	v_exp_f32_e32 v27, v27
	v_exp_f32_e32 v114, v114
	v_exp_f32_e32 v115, v115
	v_exp_f32_e32 v116, v116
	v_exp_f32_e32 v117, v117
	v_add_f32_e32 v24, 1.0, v24
	v_add_f32_e32 v25, 1.0, v25
	v_add_f32_e32 v26, 1.0, v26
	v_add_f32_e32 v27, 1.0, v27
	v_add_f32_e32 v114, 1.0, v114
	v_add_f32_e32 v115, 1.0, v115
	v_add_f32_e32 v116, 1.0, v116
	v_add_f32_e32 v117, 1.0, v117
	v_rcp_f32_e32 v24, v24
	v_rcp_f32_e32 v25, v25
	v_rcp_f32_e32 v26, v26
; __device__ __forceinline__ float bf2f(u16 h) { return __uint_as_float(((unsigned)h) << 16); }
; __device__ __forceinline__ void lru_tile(const Params& P, int chunk, int head, int pass, char* smem_raw) {
;     ...
; #pragma unroll
;       for (int tc = 0; tc < 4; ++tc)
; #pragma unroll
;         for (int reg = 0; reg < 4; ++reg) {
;           const int tl = wid * 16 + (lane >> 4) * 4 + reg;
;           const int c = 16 * tc + (lane & 15);
;           const float r = __builtin_amdgcn_rcpf(1.f + __builtin_amdgcn_exp2f(acc[tc][reg] + ba[tc]));
;           const float ii = __builtin_amdgcn_rcpf(1.f + __builtin_amdgcn_exp2f(acc[tc + 4][reg] + bi[tc]));
;           const float la = -c8[tc] * r;
;           const float a = __builtin_amdgcn_exp2f(la);
;           const float ucv = bf2f(sm_uc[(sb * 64 + tl) * LDSS + c]);
;           const float bt = __builtin_amdgcn_sqrtf(fmaxf(1.f - a * a, 0.f)) * (ii * ucv);
;           sm_a[tl * 64 + c] = a;
;           sm_b[tl * 64 + c] = bt;
;         }
;       __syncthreads();
;       const int pos = (d == 0) ? q : 3 - q;
;       {
;         float Pp = 1.f, H = 0.f;
; #pragma unroll 4
;         for (int i = 0; i < 16; ++i) {
;           const int tl = (d == 0) ? (q * 16 + i) : (q * 16 + 15 - i);
;           const float a = sm_a[tl * 64 + ch], b = sm_b[tl * 64 + ch];
;           H = a * H + b; Pp *= a;
;         }
;         sm_ph[pos * 64 + ch] = make_float2(Pp, H);
;       }
;       __syncthreads();
;       const float2 p0 = sm_ph[ch], p1 = sm_ph[64 + ch], p2 = sm_ph[128 + ch], p3 = sm_ph[192 + ch];
;       if (pass == 2) {
;         float hin = cB;
;         if (pos > 0) hin = p0.x * hin + p0.y;
;         if (pos > 1) hin = p1.x * hin + p1.y;
;         if (pos > 2) hin = p2.x * hin + p2.y;
;         float h = hin;
;         float hfp[16], gp[16];
;         if (d == 1) {
; #pragma unroll
;           for (int i = 0; i < 16; ++i) {
;             const long rowp = row0 + sb * 64 + q * 16 + 15 - i;
;             hfp[i] = hfbuf[rowp * 512 + gch];
;             gp[i] = bf2f(P.zq[rowp * 1536 + 512 + gch]);
;           }
;         }
	v_rcp_f32_e32 v27, v27
	v_rcp_f32_e32 v114, v114
	v_rcp_f32_e32 v115, v115
	v_rcp_f32_e32 v116, v116
	v_rcp_f32_e32 v117, v117
	v_mul_f32_e32 v24, v147, v24
	v_mul_f32_e32 v25, v147, v25
	v_mul_f32_e32 v26, v147, v26
	v_mul_f32_e32 v27, v147, v27
	v_mul_f32_e32 v114, v114, v186
	v_mul_f32_e32 v115, v115, v187
	v_mul_f32_e32 v116, v116, v188
	v_mul_f32_e32 v117, v117, v189
	v_exp_f32_e32 v24, v24
	v_exp_f32_e32 v25, v25
	v_exp_f32_e32 v26, v26
	v_exp_f32_e32 v27, v27
	s_nop 0
	v_fma_f32 v138, -v24, v24, 1.0 clamp
	v_fma_f32 v139, -v25, v25, 1.0 clamp
	v_fma_f32 v140, -v26, v26, 1.0 clamp
	v_fma_f32 v141, -v27, v27, 1.0 clamp
	v_sqrt_f32_e32 v138, v138
	v_sqrt_f32_e32 v139, v139
	v_sqrt_f32_e32 v140, v140
	v_sqrt_f32_e32 v141, v141
	s_nop 0
	v_mul_f32_e32 v114, v138, v114
	v_mul_f32_e32 v115, v139, v115
	v_mul_f32_e32 v116, v140, v116
	v_mul_f32_e32 v117, v141, v117
	v_add_f32_e32 v28, v28, v145
	v_add_f32_e32 v29, v29, v145
	v_add_f32_e32 v30, v30, v145
	v_add_f32_e32 v31, v31, v145
	v_add_f32_e32 v118, v118, v146
	v_add_f32_e32 v119, v119, v146
	v_add_f32_e32 v120, v120, v146
	v_add_f32_e32 v121, v121, v146
	v_exp_f32_e32 v28, v28
	v_exp_f32_e32 v29, v29
	v_exp_f32_e32 v30, v30
	v_exp_f32_e32 v31, v31
	v_exp_f32_e32 v118, v118
	v_exp_f32_e32 v119, v119
	v_exp_f32_e32 v120, v120
	v_exp_f32_e32 v121, v121
	v_add_f32_e32 v28, 1.0, v28
	v_add_f32_e32 v29, 1.0, v29
	v_add_f32_e32 v30, 1.0, v30
	v_add_f32_e32 v31, 1.0, v31
	v_add_f32_e32 v118, 1.0, v118
	v_add_f32_e32 v119, 1.0, v119
	v_add_f32_e32 v120, 1.0, v120
	v_add_f32_e32 v121, 1.0, v121
	v_rcp_f32_e32 v28, v28
	v_rcp_f32_e32 v29, v29
	v_rcp_f32_e32 v30, v30
	v_rcp_f32_e32 v31, v31
	v_rcp_f32_e32 v118, v118
	v_rcp_f32_e32 v119, v119
	v_rcp_f32_e32 v120, v120
	v_rcp_f32_e32 v121, v121
	v_mul_f32_e32 v28, v147, v28
	v_mul_f32_e32 v29, v147, v29
	v_mul_f32_e32 v30, v147, v30
	v_mul_f32_e32 v31, v147, v31
	v_mul_f32_e32 v118, v118, v190
	v_mul_f32_e32 v119, v119, v191
	v_mul_f32_e32 v120, v120, v192
	v_mul_f32_e32 v121, v121, v193
	v_exp_f32_e32 v28, v28
	v_exp_f32_e32 v29, v29
	v_exp_f32_e32 v30, v30
	v_exp_f32_e32 v31, v31
	s_nop 0
	v_fma_f32 v138, -v28, v28, 1.0 clamp
	v_fma_f32 v139, -v29, v29, 1.0 clamp
	v_fma_f32 v140, -v30, v30, 1.0 clamp
	v_fma_f32 v141, -v31, v31, 1.0 clamp
	v_sqrt_f32_e32 v138, v138
	v_sqrt_f32_e32 v139, v139
	v_sqrt_f32_e32 v140, v140
	v_sqrt_f32_e32 v141, v141
	s_nop 0
	v_mul_f32_e32 v118, v138, v118
	v_mul_f32_e32 v119, v139, v119
	v_mul_f32_e32 v120, v140, v120
	v_mul_f32_e32 v121, v141, v121
	s_mul_i32 s0, s71, 0x60000
	s_lshl_b32 s1, s56, 1
	s_add_u32 s0, s0, s1
	s_add_u32 s0, s0, 0x400
	s_add_u32 s4, s10, s0
	s_addc_u32 s5, s11, 0
	global_load_ushort v162, v134, s[4:5]
	s_add_u32 s4, s4, 0xc00
	s_addc_u32 s5, s5, 0
	global_load_ushort v163, v134, s[4:5]
	s_add_u32 s4, s4, 0xc00
	s_addc_u32 s5, s5, 0
	global_load_ushort v164, v134, s[4:5]
	s_add_u32 s4, s4, 0xc00
	s_addc_u32 s5, s5, 0
	global_load_ushort v165, v134, s[4:5]
	s_add_u32 s4, s4, 0xc00
	s_addc_u32 s5, s5, 0
	global_load_ushort v166, v134, s[4:5]
	s_add_u32 s4, s4, 0xc00
	s_addc_u32 s5, s5, 0
	global_load_ushort v167, v134, s[4:5]
	s_add_u32 s4, s4, 0xc00
	s_addc_u32 s5, s5, 0
	global_load_ushort v168, v134, s[4:5]
	s_add_u32 s4, s4, 0xc00
	s_addc_u32 s5, s5, 0
	global_load_ushort v169, v134, s[4:5]
	s_add_u32 s4, s4, 0xc00
	s_addc_u32 s5, s5, 0
	global_load_ushort v170, v134, s[4:5]
	s_add_u32 s4, s4, 0xc00
	s_addc_u32 s5, s5, 0
	global_load_ushort v171, v134, s[4:5]
	s_add_u32 s4, s4, 0xc00
	s_addc_u32 s5, s5, 0
	global_load_ushort v172, v134, s[4:5]
	s_add_u32 s4, s4, 0xc00
	s_addc_u32 s5, s5, 0
	global_load_ushort v173, v134, s[4:5]
	s_add_u32 s4, s4, 0xc00
	s_addc_u32 s5, s5, 0
	global_load_ushort v174, v134, s[4:5]
	s_add_u32 s4, s4, 0xc00
	s_addc_u32 s5, s5, 0
	global_load_ushort v175, v134, s[4:5]
	s_add_u32 s4, s4, 0xc00
	s_addc_u32 s5, s5, 0
	global_load_ushort v176, v134, s[4:5]
	s_add_u32 s4, s4, 0xc00
	s_addc_u32 s5, s5, 0
	global_load_ushort v177, v134, s[4:5]
	s_add_u32 s4, s4, 0xc00
	s_addc_u32 s5, s5, 0
	global_load_ushort v178, v134, s[4:5]
	s_add_u32 s4, s4, 0xc00
	s_addc_u32 s5, s5, 0
	global_load_ushort v179, v134, s[4:5]
	s_add_u32 s4, s4, 0xc00
	s_addc_u32 s5, s5, 0
	global_load_ushort v180, v134, s[4:5]
	s_add_u32 s4, s4, 0xc00
	s_addc_u32 s5, s5, 0
	global_load_ushort v181, v134, s[4:5]
	s_add_u32 s4, s4, 0xc00
	s_addc_u32 s5, s5, 0
	global_load_ushort v182, v134, s[4:5]
	s_add_u32 s4, s4, 0xc00
	s_addc_u32 s5, s5, 0
	global_load_ushort v183, v134, s[4:5]
	s_add_u32 s4, s4, 0xc00
	s_addc_u32 s5, s5, 0
	global_load_ushort v184, v134, s[4:5]
	s_add_u32 s4, s4, 0xc00
	s_addc_u32 s5, s5, 0
	global_load_ushort v185, v134, s[4:5]
	s_add_u32 s4, s4, 0xc00
	s_addc_u32 s5, s5, 0
	global_load_ushort v186, v134, s[4:5]
	s_add_u32 s4, s4, 0xc00
	s_addc_u32 s5, s5, 0
	global_load_ushort v187, v134, s[4:5]
	s_add_u32 s4, s4, 0xc00
	s_addc_u32 s5, s5, 0
	global_load_ushort v188, v134, s[4:5]
	s_add_u32 s4, s4, 0xc00
	s_addc_u32 s5, s5, 0
	global_load_ushort v189, v134, s[4:5]
	s_add_u32 s4, s4, 0xc00
	s_addc_u32 s5, s5, 0
	global_load_ushort v190, v134, s[4:5]
	s_add_u32 s4, s4, 0xc00
	s_addc_u32 s5, s5, 0
	global_load_ushort v191, v134, s[4:5]
	s_add_u32 s4, s4, 0xc00
	s_addc_u32 s5, s5, 0
	global_load_ushort v192, v134, s[4:5]
	s_add_u32 s4, s4, 0xc00
	s_addc_u32 s5, s5, 0
	global_load_ushort v193, v134, s[4:5]
	v_mov_b32_e32 v253, v31
	v_mov_b32_e32 v254, v121
	v_fma_f32 v254, v30, v254, v120
	v_mul_f32_e32 v253, v253, v30
	v_fma_f32 v254, v29, v254, v119
	v_mul_f32_e32 v253, v253, v29
	v_fma_f32 v254, v28, v254, v118
	v_mul_f32_e32 v253, v253, v28
	v_fma_f32 v254, v27, v254, v117
; __device__ __forceinline__ float bf2f(u16 h) { return __uint_as_float(((unsigned)h) << 16); }
; __device__ __forceinline__ void lru_tile(const Params& P, int chunk, int head, int pass, char* smem_raw) {
;     ...
;       if (pass == 2) {
;         float hin = cB;
;         if (pos > 0) hin = p0.x * hin + p0.y;
;         if (pos > 1) hin = p1.x * hin + p1.y;
;         if (pos > 2) hin = p2.x * hin + p2.y;
;         float h = hin;
;         float hfp[16], gp[16];
;         if (d == 1) {
; #pragma unroll
;           for (int i = 0; i < 16; ++i) {
;             const long rowp = row0 + sb * 64 + q * 16 + 15 - i;
;             hfp[i] = hfbuf[rowp * 512 + gch];
;             gp[i] = bf2f(P.zq[rowp * 1536 + 512 + gch]);
;           }
;         }
; #pragma unroll
;         for (int i = 0; i < 16; ++i) {
;           const int tl = (d == 0) ? (q * 16 + i) : (q * 16 + 15 - i);
;           const float a = sm_a[tl * 64 + ch], b = sm_b[tl * 64 + ch];
;           h = a * h + b;
;           const long row = row0 + sb * 64 + tl;
;           if (d == 0) {
;             hfw[row * 512 + gch] = h;
;           } else {
;             const float hfv = hfp[i];
;             const float g = gp[i];
;             const float tz = 0.7978845608028654f * (g + 0.044715f * g * g * g);
;             const float th = 1.f - 2.f * __builtin_amdgcn_rcpf(1.f + __expf(2.f * tz));
	v_mul_f32_e32 v253, v253, v27
	v_fma_f32 v254, v26, v254, v116
	v_mul_f32_e32 v253, v253, v26
	v_fma_f32 v254, v25, v254, v115
	v_mul_f32_e32 v253, v253, v25
	v_fma_f32 v254, v24, v254, v114
	v_mul_f32_e32 v253, v253, v24
	v_fma_f32 v254, v23, v254, v113
	v_mul_f32_e32 v253, v253, v23
	v_fma_f32 v254, v22, v254, v112
	v_mul_f32_e32 v253, v253, v22
	v_fma_f32 v254, v21, v254, v111
	v_mul_f32_e32 v253, v253, v21
	v_fma_f32 v254, v20, v254, v110
	v_mul_f32_e32 v253, v253, v20
	v_fma_f32 v254, v19, v254, v109
	v_mul_f32_e32 v253, v253, v19
	v_fma_f32 v254, v18, v254, v108
	v_mul_f32_e32 v253, v253, v18
	v_fma_f32 v254, v17, v254, v107
	v_mul_f32_e32 v253, v253, v17
	v_fma_f32 v254, v16, v254, v106
	v_mul_f32_e32 v253, v253, v16
	v_fma_f32 v254, v15, v254, v105
	v_mul_f32_e32 v253, v253, v15
	v_fma_f32 v254, v14, v254, v104
	v_mul_f32_e32 v253, v253, v14
	v_fma_f32 v254, v13, v254, v103
	v_mul_f32_e32 v253, v253, v13
	v_fma_f32 v254, v12, v254, v102
	v_mul_f32_e32 v253, v253, v12
	v_fma_f32 v254, v11, v254, v101
	v_mul_f32_e32 v253, v253, v11
	v_fma_f32 v254, v10, v254, v100
	v_mul_f32_e32 v253, v253, v10
	v_fma_f32 v254, v9, v254, v99
	v_mul_f32_e32 v253, v253, v9
	v_fma_f32 v254, v8, v254, v98
	v_mul_f32_e32 v253, v253, v8
	v_fma_f32 v254, v7, v254, v97
	v_mul_f32_e32 v253, v253, v7
	v_fma_f32 v254, v6, v254, v96
	v_mul_f32_e32 v253, v253, v6
	v_fma_f32 v254, v5, v254, v95
	v_mul_f32_e32 v253, v253, v5
	v_fma_f32 v254, v4, v254, v94
	v_mul_f32_e32 v253, v253, v4
	v_fma_f32 v254, v3, v254, v93
	v_mul_f32_e32 v253, v253, v3
	v_fma_f32 v254, v2, v254, v92
	v_mul_f32_e32 v253, v253, v2
	v_fma_f32 v254, v1, v254, v91
	v_mul_f32_e32 v253, v253, v1
	v_fma_f32 v254, v0, v254, v90
	v_mul_f32_e32 v253, v253, v0
	v_mov_b32_e32 v138, v253
	v_mov_b32_e32 v139, v253
	s_nop 1
	v_permlane16_swap_b32_e32 v138, v139
	v_mov_b32_e32 v140, v138
	v_mov_b32_e32 v141, v139
	s_nop 1
	v_permlane32_swap_b32_e32 v138, v140
	v_permlane32_swap_b32_e32 v139, v141
	v_mov_b32_e32 v198, v254
	v_mov_b32_e32 v199, v254
	s_nop 1
	v_permlane16_swap_b32_e32 v198, v199
	v_mov_b32_e32 v200, v198
	v_mov_b32_e32 v201, v199
	s_nop 1
	v_permlane32_swap_b32_e32 v198, v200
	v_permlane32_swap_b32_e32 v199, v201
	v_mov_b32_e32 v202, v149
	v_fma_f32 v151, v141, v202, v201
	v_fma_f32 v150, v140, v151, v200
	v_fma_f32 v136, v139, v150, v199
	v_mov_b32_e32 v254, v202
	v_cndmask_b32_e64 v254, v254, v151, s[78:79]
	v_cndmask_b32_e64 v254, v254, v150, s[80:81]
	v_cndmask_b32_e64 v254, v254, v136, s[82:83]
	v_fma_f32 v121, v31, v254, v121
	v_fma_f32 v120, v30, v121, v120
	v_fma_f32 v119, v29, v120, v119
	v_fma_f32 v118, v28, v119, v118
	v_fma_f32 v117, v27, v118, v117
	v_fma_f32 v116, v26, v117, v116
	v_fma_f32 v115, v25, v116, v115
	v_fma_f32 v114, v24, v115, v114
	v_fma_f32 v113, v23, v114, v113
	v_fma_f32 v112, v22, v113, v112
	v_fma_f32 v111, v21, v112, v111
	v_fma_f32 v110, v20, v111, v110
	v_fma_f32 v109, v19, v110, v109
	v_fma_f32 v108, v18, v109, v108
	v_fma_f32 v107, v17, v108, v107
	v_fma_f32 v106, v16, v107, v106
	v_fma_f32 v105, v15, v106, v105
	v_fma_f32 v104, v14, v105, v104
	v_fma_f32 v103, v13, v104, v103
	v_fma_f32 v102, v12, v103, v102
	v_fma_f32 v101, v11, v102, v101
	v_fma_f32 v100, v10, v101, v100
	v_fma_f32 v99, v9, v100, v99
	v_fma_f32 v98, v8, v99, v98
	v_fma_f32 v97, v7, v98, v97
	v_fma_f32 v96, v6, v97, v96
	v_fma_f32 v95, v5, v96, v95
	v_fma_f32 v94, v4, v95, v94
	v_fma_f32 v93, v3, v94, v93
	v_fma_f32 v92, v2, v93, v92
	v_fma_f32 v91, v1, v92, v91
	v_fma_f32 v90, v0, v91, v90
	s_waitcnt vmcnt(0)
	v_lshlrev_b32_e32 v162, 16, v162
	v_lshlrev_b32_e32 v163, 16, v163
	v_lshlrev_b32_e32 v164, 16, v164
	v_lshlrev_b32_e32 v165, 16, v165
	v_lshlrev_b32_e32 v166, 16, v166
	v_lshlrev_b32_e32 v167, 16, v167
	v_lshlrev_b32_e32 v168, 16, v168
	v_lshlrev_b32_e32 v169, 16, v169
	v_lshlrev_b32_e32 v170, 16, v170
	v_lshlrev_b32_e32 v171, 16, v171
	v_lshlrev_b32_e32 v172, 16, v172
	v_lshlrev_b32_e32 v173, 16, v173
	v_lshlrev_b32_e32 v174, 16, v174
	v_lshlrev_b32_e32 v175, 16, v175
	v_lshlrev_b32_e32 v176, 16, v176
	v_lshlrev_b32_e32 v177, 16, v177
	v_lshlrev_b32_e32 v178, 16, v178
	v_lshlrev_b32_e32 v179, 16, v179
	v_lshlrev_b32_e32 v180, 16, v180
	v_lshlrev_b32_e32 v181, 16, v181
	v_lshlrev_b32_e32 v182, 16, v182
	v_lshlrev_b32_e32 v183, 16, v183
	v_lshlrev_b32_e32 v184, 16, v184
	v_lshlrev_b32_e32 v185, 16, v185
	v_lshlrev_b32_e32 v186, 16, v186
	v_lshlrev_b32_e32 v187, 16, v187
	v_lshlrev_b32_e32 v188, 16, v188
	v_lshlrev_b32_e32 v189, 16, v189
	v_lshlrev_b32_e32 v190, 16, v190
	v_lshlrev_b32_e32 v191, 16, v191
	v_lshlrev_b32_e32 v192, 16, v192
	v_lshlrev_b32_e32 v193, 16, v193
	v_mov_b32_e32 v202, 0x3d372713
	v_mul_f32_e32 v138, v162, v162
	v_mul_f32_e32 v139, v163, v163
	v_mul_f32_e32 v140, v164, v164
	v_mul_f32_e32 v141, v165, v165
	v_mul_f32_e32 v138, v138, v162
	v_mul_f32_e32 v139, v139, v163
	v_mul_f32_e32 v140, v140, v164
	v_mul_f32_e32 v141, v141, v165
	v_fma_f32 v138, v202, v138, v162
	v_fma_f32 v139, v202, v139, v163
	v_fma_f32 v140, v202, v140, v164
	v_fma_f32 v141, v202, v141, v165
	v_mul_f32_e32 v138, 0x40135761, v138
	v_mul_f32_e32 v139, 0x40135761, v139
	v_mul_f32_e32 v140, 0x40135761, v140
	v_mul_f32_e32 v141, 0x40135761, v141
	v_exp_f32_e32 v138, v138
	v_exp_f32_e32 v139, v139
	v_exp_f32_e32 v140, v140
	v_exp_f32_e32 v141, v141
	s_nop 0
	v_add_f32_e32 v138, 1.0, v138
	v_add_f32_e32 v139, 1.0, v139
	v_add_f32_e32 v140, 1.0, v140
	v_add_f32_e32 v141, 1.0, v141
	v_rcp_f32_e32 v138, v138
	v_rcp_f32_e32 v139, v139
	v_rcp_f32_e32 v140, v140
	v_rcp_f32_e32 v141, v141
	s_nop 0
	v_fma_f32 v138, -2.0, v138, 1.0
	v_fma_f32 v139, -2.0, v139, 1.0
	v_fma_f32 v140, -2.0, v140, 1.0
; __device__ __forceinline__ void lru_tile(const Params& P, int chunk, int head, int pass, char* smem_raw) {
;     ...
;             const float hfv = hfp[i];
;             const float g = gp[i];
;             const float tz = 0.7978845608028654f * (g + 0.044715f * g * g * g);
;             const float th = 1.f - 2.f * __builtin_amdgcn_rcpf(1.f + __expf(2.f * tz));
;             const float ge = 0.5f * g * (1.f + th);
;             P.cat[row * 1024 + gch] = f2bf((hfv + h) * ge);
	v_fma_f32 v141, -2.0, v141, 1.0
	v_add_f32_e32 v138, 1.0, v138
	v_add_f32_e32 v139, 1.0, v139
	v_add_f32_e32 v140, 1.0, v140
	v_add_f32_e32 v141, 1.0, v141
	v_mul_f32_e32 v162, 0.5, v162
	v_mul_f32_e32 v163, 0.5, v163
	v_mul_f32_e32 v164, 0.5, v164
	v_mul_f32_e32 v165, 0.5, v165
	v_mul_f32_e32 v162, v162, v138
	v_mul_f32_e32 v163, v163, v139
	v_mul_f32_e32 v164, v164, v140
	v_mul_f32_e32 v165, v165, v141
	v_add_f32_e32 v90, v205, v90
	v_add_f32_e32 v91, v206, v91
	v_add_f32_e32 v92, v207, v92
	v_add_f32_e32 v93, v208, v93
	v_mul_f32_e32 v90, v90, v162
	v_mul_f32_e32 v91, v91, v163
	v_mul_f32_e32 v92, v92, v164
	v_mul_f32_e32 v93, v93, v165
	v_cvt_pk_bf16_f32 v90, v90, v90
	v_cvt_pk_bf16_f32 v91, v91, v91
	v_cvt_pk_bf16_f32 v92, v92, v92
	v_cvt_pk_bf16_f32 v93, v93, v93
	v_mul_f32_e32 v138, v166, v166
	v_mul_f32_e32 v139, v167, v167
	v_mul_f32_e32 v140, v168, v168
	v_mul_f32_e32 v141, v169, v169
	v_mul_f32_e32 v138, v138, v166
	v_mul_f32_e32 v139, v139, v167
	v_mul_f32_e32 v140, v140, v168
	v_mul_f32_e32 v141, v141, v169
	v_fma_f32 v138, v202, v138, v166
	v_fma_f32 v139, v202, v139, v167
	v_fma_f32 v140, v202, v140, v168
	v_fma_f32 v141, v202, v141, v169
	v_mul_f32_e32 v138, 0x40135761, v138
	v_mul_f32_e32 v139, 0x40135761, v139
	v_mul_f32_e32 v140, 0x40135761, v140
	v_mul_f32_e32 v141, 0x40135761, v141
	v_exp_f32_e32 v138, v138
	v_exp_f32_e32 v139, v139
	v_exp_f32_e32 v140, v140
	v_exp_f32_e32 v141, v141
	s_nop 0
	v_add_f32_e32 v138, 1.0, v138
	v_add_f32_e32 v139, 1.0, v139
	v_add_f32_e32 v140, 1.0, v140
	v_add_f32_e32 v141, 1.0, v141
	v_rcp_f32_e32 v138, v138
	v_rcp_f32_e32 v139, v139
	v_rcp_f32_e32 v140, v140
	v_rcp_f32_e32 v141, v141
	s_nop 0
	v_fma_f32 v138, -2.0, v138, 1.0
	v_fma_f32 v139, -2.0, v139, 1.0
	v_fma_f32 v140, -2.0, v140, 1.0
	v_fma_f32 v141, -2.0, v141, 1.0
	v_add_f32_e32 v138, 1.0, v138
	v_add_f32_e32 v139, 1.0, v139
	v_add_f32_e32 v140, 1.0, v140
	v_add_f32_e32 v141, 1.0, v141
	v_mul_f32_e32 v166, 0.5, v166
	v_mul_f32_e32 v167, 0.5, v167
	v_mul_f32_e32 v168, 0.5, v168
	v_mul_f32_e32 v169, 0.5, v169
	v_mul_f32_e32 v166, v166, v138
	v_mul_f32_e32 v167, v167, v139
	v_mul_f32_e32 v168, v168, v140
	v_mul_f32_e32 v169, v169, v141
	v_add_f32_e32 v94, v209, v94
	v_add_f32_e32 v95, v210, v95
	v_add_f32_e32 v96, v211, v96
	v_add_f32_e32 v97, v212, v97
	v_mul_f32_e32 v94, v94, v166
	v_mul_f32_e32 v95, v95, v167
	v_mul_f32_e32 v96, v96, v168
	v_mul_f32_e32 v97, v97, v169
	v_cvt_pk_bf16_f32 v94, v94, v94
	v_cvt_pk_bf16_f32 v95, v95, v95
	v_cvt_pk_bf16_f32 v96, v96, v96
	v_cvt_pk_bf16_f32 v97, v97, v97
	v_mul_f32_e32 v138, v170, v170
	v_mul_f32_e32 v139, v171, v171
	v_mul_f32_e32 v140, v172, v172
	v_mul_f32_e32 v141, v173, v173
	v_mul_f32_e32 v138, v138, v170
	v_mul_f32_e32 v139, v139, v171
	v_mul_f32_e32 v140, v140, v172
	v_mul_f32_e32 v141, v141, v173
	v_fma_f32 v138, v202, v138, v170
	v_fma_f32 v139, v202, v139, v171
	v_fma_f32 v140, v202, v140, v172
	v_fma_f32 v141, v202, v141, v173
	v_mul_f32_e32 v138, 0x40135761, v138
	v_mul_f32_e32 v139, 0x40135761, v139
	v_mul_f32_e32 v140, 0x40135761, v140
	v_mul_f32_e32 v141, 0x40135761, v141
	v_exp_f32_e32 v138, v138
	v_exp_f32_e32 v139, v139
	v_exp_f32_e32 v140, v140
	v_exp_f32_e32 v141, v141
	s_nop 0
	v_add_f32_e32 v138, 1.0, v138
	v_add_f32_e32 v139, 1.0, v139
	v_add_f32_e32 v140, 1.0, v140
	v_add_f32_e32 v141, 1.0, v141
	v_rcp_f32_e32 v138, v138
	v_rcp_f32_e32 v139, v139
	v_rcp_f32_e32 v140, v140
	v_rcp_f32_e32 v141, v141
	s_nop 0
	v_fma_f32 v138, -2.0, v138, 1.0
	v_fma_f32 v139, -2.0, v139, 1.0
	v_fma_f32 v140, -2.0, v140, 1.0
	v_fma_f32 v141, -2.0, v141, 1.0
	v_add_f32_e32 v138, 1.0, v138
	v_add_f32_e32 v139, 1.0, v139
	v_add_f32_e32 v140, 1.0, v140
	v_add_f32_e32 v141, 1.0, v141
	v_mul_f32_e32 v170, 0.5, v170
	v_mul_f32_e32 v171, 0.5, v171
	v_mul_f32_e32 v172, 0.5, v172
	v_mul_f32_e32 v173, 0.5, v173
	v_mul_f32_e32 v170, v170, v138
	v_mul_f32_e32 v171, v171, v139
	v_mul_f32_e32 v172, v172, v140
	v_mul_f32_e32 v173, v173, v141
	v_add_f32_e32 v98, v213, v98
	v_add_f32_e32 v99, v214, v99
	v_add_f32_e32 v100, v215, v100
	v_add_f32_e32 v101, v216, v101
	v_mul_f32_e32 v98, v98, v170
	v_mul_f32_e32 v99, v99, v171
	v_mul_f32_e32 v100, v100, v172
	v_mul_f32_e32 v101, v101, v173
	v_cvt_pk_bf16_f32 v98, v98, v98
	v_cvt_pk_bf16_f32 v99, v99, v99
	v_cvt_pk_bf16_f32 v100, v100, v100
	v_cvt_pk_bf16_f32 v101, v101, v101
	v_mul_f32_e32 v138, v174, v174
	v_mul_f32_e32 v139, v175, v175
	v_mul_f32_e32 v140, v176, v176
	v_mul_f32_e32 v141, v177, v177
	v_mul_f32_e32 v138, v138, v174
	v_mul_f32_e32 v139, v139, v175
	v_mul_f32_e32 v140, v140, v176
	v_mul_f32_e32 v141, v141, v177
	v_fma_f32 v138, v202, v138, v174
	v_fma_f32 v139, v202, v139, v175
	v_fma_f32 v140, v202, v140, v176
	v_fma_f32 v141, v202, v141, v177
	v_mul_f32_e32 v138, 0x40135761, v138
	v_mul_f32_e32 v139, 0x40135761, v139
	v_mul_f32_e32 v140, 0x40135761, v140
	v_mul_f32_e32 v141, 0x40135761, v141
	v_exp_f32_e32 v138, v138
	v_exp_f32_e32 v139, v139
	v_exp_f32_e32 v140, v140
	v_exp_f32_e32 v141, v141
	s_nop 0
	v_add_f32_e32 v138, 1.0, v138
	v_add_f32_e32 v139, 1.0, v139
	v_add_f32_e32 v140, 1.0, v140
	v_add_f32_e32 v141, 1.0, v141
	v_rcp_f32_e32 v138, v138
	v_rcp_f32_e32 v139, v139
	v_rcp_f32_e32 v140, v140
	v_rcp_f32_e32 v141, v141
	s_nop 0
	v_fma_f32 v138, -2.0, v138, 1.0
	v_fma_f32 v139, -2.0, v139, 1.0
	v_fma_f32 v140, -2.0, v140, 1.0
	v_fma_f32 v141, -2.0, v141, 1.0
	v_add_f32_e32 v138, 1.0, v138
	v_add_f32_e32 v139, 1.0, v139
	v_add_f32_e32 v140, 1.0, v140
	v_add_f32_e32 v141, 1.0, v141
	v_mul_f32_e32 v174, 0.5, v174
	v_mul_f32_e32 v175, 0.5, v175
	v_mul_f32_e32 v176, 0.5, v176
	v_mul_f32_e32 v177, 0.5, v177
	v_mul_f32_e32 v174, v174, v138
; __device__ __forceinline__ void lru_tile(const Params& P, int chunk, int head, int pass, char* smem_raw) {
;     ...
;             const float hfv = hfp[i];
;             const float g = gp[i];
;             const float tz = 0.7978845608028654f * (g + 0.044715f * g * g * g);
;             const float th = 1.f - 2.f * __builtin_amdgcn_rcpf(1.f + __expf(2.f * tz));
;             const float ge = 0.5f * g * (1.f + th);
;             P.cat[row * 1024 + gch] = f2bf((hfv + h) * ge);
	v_mul_f32_e32 v175, v175, v139
	v_mul_f32_e32 v176, v176, v140
	v_mul_f32_e32 v177, v177, v141
	v_add_f32_e32 v102, v217, v102
	v_add_f32_e32 v103, v218, v103
	v_add_f32_e32 v104, v219, v104
	v_add_f32_e32 v105, v220, v105
	v_mul_f32_e32 v102, v102, v174
	v_mul_f32_e32 v103, v103, v175
	v_mul_f32_e32 v104, v104, v176
	v_mul_f32_e32 v105, v105, v177
	v_cvt_pk_bf16_f32 v102, v102, v102
	v_cvt_pk_bf16_f32 v103, v103, v103
	v_cvt_pk_bf16_f32 v104, v104, v104
	v_cvt_pk_bf16_f32 v105, v105, v105
	v_mul_f32_e32 v138, v178, v178
	v_mul_f32_e32 v139, v179, v179
	v_mul_f32_e32 v140, v180, v180
	v_mul_f32_e32 v141, v181, v181
	v_mul_f32_e32 v138, v138, v178
	v_mul_f32_e32 v139, v139, v179
	v_mul_f32_e32 v140, v140, v180
	v_mul_f32_e32 v141, v141, v181
	v_fma_f32 v138, v202, v138, v178
	v_fma_f32 v139, v202, v139, v179
	v_fma_f32 v140, v202, v140, v180
	v_fma_f32 v141, v202, v141, v181
	v_mul_f32_e32 v138, 0x40135761, v138
	v_mul_f32_e32 v139, 0x40135761, v139
	v_mul_f32_e32 v140, 0x40135761, v140
	v_mul_f32_e32 v141, 0x40135761, v141
	v_exp_f32_e32 v138, v138
	v_exp_f32_e32 v139, v139
	v_exp_f32_e32 v140, v140
	v_exp_f32_e32 v141, v141
	s_nop 0
	v_add_f32_e32 v138, 1.0, v138
	v_add_f32_e32 v139, 1.0, v139
	v_add_f32_e32 v140, 1.0, v140
	v_add_f32_e32 v141, 1.0, v141
	v_rcp_f32_e32 v138, v138
	v_rcp_f32_e32 v139, v139
	v_rcp_f32_e32 v140, v140
	v_rcp_f32_e32 v141, v141
	s_nop 0
	v_fma_f32 v138, -2.0, v138, 1.0
	v_fma_f32 v139, -2.0, v139, 1.0
	v_fma_f32 v140, -2.0, v140, 1.0
	v_fma_f32 v141, -2.0, v141, 1.0
	v_add_f32_e32 v138, 1.0, v138
	v_add_f32_e32 v139, 1.0, v139
	v_add_f32_e32 v140, 1.0, v140
	v_add_f32_e32 v141, 1.0, v141
	v_mul_f32_e32 v178, 0.5, v178
	v_mul_f32_e32 v179, 0.5, v179
	v_mul_f32_e32 v180, 0.5, v180
	v_mul_f32_e32 v181, 0.5, v181
	v_mul_f32_e32 v178, v178, v138
	v_mul_f32_e32 v179, v179, v139
	v_mul_f32_e32 v180, v180, v140
	v_mul_f32_e32 v181, v181, v141
	v_add_f32_e32 v106, v221, v106
	v_add_f32_e32 v107, v222, v107
	v_add_f32_e32 v108, v223, v108
	v_add_f32_e32 v109, v224, v109
	v_mul_f32_e32 v106, v106, v178
	v_mul_f32_e32 v107, v107, v179
	v_mul_f32_e32 v108, v108, v180
	v_mul_f32_e32 v109, v109, v181
	v_cvt_pk_bf16_f32 v106, v106, v106
	v_cvt_pk_bf16_f32 v107, v107, v107
	v_cvt_pk_bf16_f32 v108, v108, v108
	v_cvt_pk_bf16_f32 v109, v109, v109
	v_mul_f32_e32 v138, v182, v182
	v_mul_f32_e32 v139, v183, v183
	v_mul_f32_e32 v140, v184, v184
	v_mul_f32_e32 v141, v185, v185
	v_mul_f32_e32 v138, v138, v182
	v_mul_f32_e32 v139, v139, v183
	v_mul_f32_e32 v140, v140, v184
	v_mul_f32_e32 v141, v141, v185
	v_fma_f32 v138, v202, v138, v182
	v_fma_f32 v139, v202, v139, v183
	v_fma_f32 v140, v202, v140, v184
	v_fma_f32 v141, v202, v141, v185
	v_mul_f32_e32 v138, 0x40135761, v138
	v_mul_f32_e32 v139, 0x40135761, v139
	v_mul_f32_e32 v140, 0x40135761, v140
	v_mul_f32_e32 v141, 0x40135761, v141
	v_exp_f32_e32 v138, v138
	v_exp_f32_e32 v139, v139
	v_exp_f32_e32 v140, v140
	v_exp_f32_e32 v141, v141
	s_nop 0
	v_add_f32_e32 v138, 1.0, v138
	v_add_f32_e32 v139, 1.0, v139
	v_add_f32_e32 v140, 1.0, v140
	v_add_f32_e32 v141, 1.0, v141
	v_rcp_f32_e32 v138, v138
	v_rcp_f32_e32 v139, v139
	v_rcp_f32_e32 v140, v140
	v_rcp_f32_e32 v141, v141
	s_nop 0
	v_fma_f32 v138, -2.0, v138, 1.0
	v_fma_f32 v139, -2.0, v139, 1.0
	v_fma_f32 v140, -2.0, v140, 1.0
	v_fma_f32 v141, -2.0, v141, 1.0
	v_add_f32_e32 v138, 1.0, v138
	v_add_f32_e32 v139, 1.0, v139
	v_add_f32_e32 v140, 1.0, v140
	v_add_f32_e32 v141, 1.0, v141
	v_mul_f32_e32 v182, 0.5, v182
	v_mul_f32_e32 v183, 0.5, v183
	v_mul_f32_e32 v184, 0.5, v184
	v_mul_f32_e32 v185, 0.5, v185
	v_mul_f32_e32 v182, v182, v138
	v_mul_f32_e32 v183, v183, v139
	v_mul_f32_e32 v184, v184, v140
	v_mul_f32_e32 v185, v185, v141
	v_add_f32_e32 v110, v225, v110
	v_add_f32_e32 v111, v226, v111
	v_add_f32_e32 v112, v227, v112
	v_add_f32_e32 v113, v228, v113
	v_mul_f32_e32 v110, v110, v182
	v_mul_f32_e32 v111, v111, v183
	v_mul_f32_e32 v112, v112, v184
	v_mul_f32_e32 v113, v113, v185
	v_cvt_pk_bf16_f32 v110, v110, v110
	v_cvt_pk_bf16_f32 v111, v111, v111
	v_cvt_pk_bf16_f32 v112, v112, v112
	v_cvt_pk_bf16_f32 v113, v113, v113
	v_mul_f32_e32 v138, v186, v186
	v_mul_f32_e32 v139, v187, v187
	v_mul_f32_e32 v140, v188, v188
	v_mul_f32_e32 v141, v189, v189
	v_mul_f32_e32 v138, v138, v186
	v_mul_f32_e32 v139, v139, v187
	v_mul_f32_e32 v140, v140, v188
	v_mul_f32_e32 v141, v141, v189
	v_fma_f32 v138, v202, v138, v186
	v_fma_f32 v139, v202, v139, v187
	v_fma_f32 v140, v202, v140, v188
	v_fma_f32 v141, v202, v141, v189
	v_mul_f32_e32 v138, 0x40135761, v138
	v_mul_f32_e32 v139, 0x40135761, v139
	v_mul_f32_e32 v140, 0x40135761, v140
	v_mul_f32_e32 v141, 0x40135761, v141
	v_exp_f32_e32 v138, v138
	v_exp_f32_e32 v139, v139
	v_exp_f32_e32 v140, v140
	v_exp_f32_e32 v141, v141
	s_nop 0
	v_add_f32_e32 v138, 1.0, v138
	v_add_f32_e32 v139, 1.0, v139
	v_add_f32_e32 v140, 1.0, v140
	v_add_f32_e32 v141, 1.0, v141
	v_rcp_f32_e32 v138, v138
	v_rcp_f32_e32 v139, v139
	v_rcp_f32_e32 v140, v140
	v_rcp_f32_e32 v141, v141
	s_nop 0
	v_fma_f32 v138, -2.0, v138, 1.0
	v_fma_f32 v139, -2.0, v139, 1.0
	v_fma_f32 v140, -2.0, v140, 1.0
	v_fma_f32 v141, -2.0, v141, 1.0
	v_add_f32_e32 v138, 1.0, v138
	v_add_f32_e32 v139, 1.0, v139
	v_add_f32_e32 v140, 1.0, v140
	v_add_f32_e32 v141, 1.0, v141
	v_mul_f32_e32 v186, 0.5, v186
	v_mul_f32_e32 v187, 0.5, v187
	v_mul_f32_e32 v188, 0.5, v188
	v_mul_f32_e32 v189, 0.5, v189
	v_mul_f32_e32 v186, v186, v138
; __device__ __forceinline__ void lru_tile(const Params& P, int chunk, int head, int pass, char* smem_raw) {
;     ...
;             const float hfv = hfp[i];
;             const float g = gp[i];
;             const float tz = 0.7978845608028654f * (g + 0.044715f * g * g * g);
;             const float th = 1.f - 2.f * __builtin_amdgcn_rcpf(1.f + __expf(2.f * tz));
;             const float ge = 0.5f * g * (1.f + th);
;             P.cat[row * 1024 + gch] = f2bf((hfv + h) * ge);
;           }
;         }
	v_mul_f32_e32 v187, v187, v139
	v_mul_f32_e32 v188, v188, v140
	v_mul_f32_e32 v189, v189, v141
	v_add_f32_e32 v114, v229, v114
	v_add_f32_e32 v115, v230, v115
	v_add_f32_e32 v116, v231, v116
	v_add_f32_e32 v117, v232, v117
	v_mul_f32_e32 v114, v114, v186
	v_mul_f32_e32 v115, v115, v187
	v_mul_f32_e32 v116, v116, v188
	v_mul_f32_e32 v117, v117, v189
	v_cvt_pk_bf16_f32 v114, v114, v114
	v_cvt_pk_bf16_f32 v115, v115, v115
	v_cvt_pk_bf16_f32 v116, v116, v116
	v_cvt_pk_bf16_f32 v117, v117, v117
	v_mul_f32_e32 v138, v190, v190
	v_mul_f32_e32 v139, v191, v191
	v_mul_f32_e32 v140, v192, v192
	v_mul_f32_e32 v141, v193, v193
	v_mul_f32_e32 v138, v138, v190
	v_mul_f32_e32 v139, v139, v191
	v_mul_f32_e32 v140, v140, v192
	v_mul_f32_e32 v141, v141, v193
	v_fma_f32 v138, v202, v138, v190
	v_fma_f32 v139, v202, v139, v191
	v_fma_f32 v140, v202, v140, v192
	v_fma_f32 v141, v202, v141, v193
	v_mul_f32_e32 v138, 0x40135761, v138
	v_mul_f32_e32 v139, 0x40135761, v139
	v_mul_f32_e32 v140, 0x40135761, v140
	v_mul_f32_e32 v141, 0x40135761, v141
	v_exp_f32_e32 v138, v138
	v_exp_f32_e32 v139, v139
	v_exp_f32_e32 v140, v140
	v_exp_f32_e32 v141, v141
	s_nop 0
	v_add_f32_e32 v138, 1.0, v138
	v_add_f32_e32 v139, 1.0, v139
	v_add_f32_e32 v140, 1.0, v140
	v_add_f32_e32 v141, 1.0, v141
	v_rcp_f32_e32 v138, v138
	v_rcp_f32_e32 v139, v139
	v_rcp_f32_e32 v140, v140
	v_rcp_f32_e32 v141, v141
	s_nop 0
	v_fma_f32 v138, -2.0, v138, 1.0
	v_fma_f32 v139, -2.0, v139, 1.0
	v_fma_f32 v140, -2.0, v140, 1.0
	v_fma_f32 v141, -2.0, v141, 1.0
	v_add_f32_e32 v138, 1.0, v138
	v_add_f32_e32 v139, 1.0, v139
	v_add_f32_e32 v140, 1.0, v140
	v_add_f32_e32 v141, 1.0, v141
	v_mul_f32_e32 v190, 0.5, v190
	v_mul_f32_e32 v191, 0.5, v191
	v_mul_f32_e32 v192, 0.5, v192
	v_mul_f32_e32 v193, 0.5, v193
	v_mul_f32_e32 v190, v190, v138
	v_mul_f32_e32 v191, v191, v139
	v_mul_f32_e32 v192, v192, v140
	v_mul_f32_e32 v193, v193, v141
	v_add_f32_e32 v118, v233, v118
	v_add_f32_e32 v119, v234, v119
	v_add_f32_e32 v120, v235, v120
	v_add_f32_e32 v121, v236, v121
	v_mul_f32_e32 v118, v118, v190
	v_mul_f32_e32 v119, v119, v191
	v_mul_f32_e32 v120, v120, v192
	v_mul_f32_e32 v121, v121, v193
	v_cvt_pk_bf16_f32 v118, v118, v118
	v_cvt_pk_bf16_f32 v119, v119, v119
	v_cvt_pk_bf16_f32 v120, v120, v120
	v_cvt_pk_bf16_f32 v121, v121, v121
	s_lshl_b32 s0, s71, 18
	s_lshl_b32 s1, s56, 1
	s_add_u32 s0, s0, s1
	s_add_u32 s4, s12, s0
	s_addc_u32 s5, s13, 0
	global_store_short v237, v90, s[4:5]
	s_add_u32 s4, s4, 0x800
	s_addc_u32 s5, s5, 0
	global_store_short v237, v91, s[4:5]
	s_add_u32 s4, s4, 0x800
	s_addc_u32 s5, s5, 0
	global_store_short v237, v92, s[4:5]
	s_add_u32 s4, s4, 0x800
	s_addc_u32 s5, s5, 0
	global_store_short v237, v93, s[4:5]
	s_add_u32 s4, s4, 0x800
	s_addc_u32 s5, s5, 0
	global_store_short v237, v94, s[4:5]
	s_add_u32 s4, s4, 0x800
	s_addc_u32 s5, s5, 0
	global_store_short v237, v95, s[4:5]
	s_add_u32 s4, s4, 0x800
	s_addc_u32 s5, s5, 0
	global_store_short v237, v96, s[4:5]
	s_add_u32 s4, s4, 0x800
	s_addc_u32 s5, s5, 0
	global_store_short v237, v97, s[4:5]
	s_add_u32 s4, s4, 0x800
	s_addc_u32 s5, s5, 0
	global_store_short v237, v98, s[4:5]
	s_add_u32 s4, s4, 0x800
	s_addc_u32 s5, s5, 0
	global_store_short v237, v99, s[4:5]
	s_add_u32 s4, s4, 0x800
	s_addc_u32 s5, s5, 0
	global_store_short v237, v100, s[4:5]
	s_add_u32 s4, s4, 0x800
	s_addc_u32 s5, s5, 0
	global_store_short v237, v101, s[4:5]
	s_add_u32 s4, s4, 0x800
	s_addc_u32 s5, s5, 0
	global_store_short v237, v102, s[4:5]
	s_add_u32 s4, s4, 0x800
	s_addc_u32 s5, s5, 0
	global_store_short v237, v103, s[4:5]
	s_add_u32 s4, s4, 0x800
	s_addc_u32 s5, s5, 0
	global_store_short v237, v104, s[4:5]
	s_add_u32 s4, s4, 0x800
	s_addc_u32 s5, s5, 0
	global_store_short v237, v105, s[4:5]
	s_add_u32 s4, s4, 0x800
	s_addc_u32 s5, s5, 0
	global_store_short v237, v106, s[4:5]
	s_add_u32 s4, s4, 0x800
	s_addc_u32 s5, s5, 0
	global_store_short v237, v107, s[4:5]
	s_add_u32 s4, s4, 0x800
	s_addc_u32 s5, s5, 0
	global_store_short v237, v108, s[4:5]
	s_add_u32 s4, s4, 0x800
	s_addc_u32 s5, s5, 0
	global_store_short v237, v109, s[4:5]
	s_add_u32 s4, s4, 0x800
	s_addc_u32 s5, s5, 0
	global_store_short v237, v110, s[4:5]
	s_add_u32 s4, s4, 0x800
	s_addc_u32 s5, s5, 0
	global_store_short v237, v111, s[4:5]
	s_add_u32 s4, s4, 0x800
	s_addc_u32 s5, s5, 0
	global_store_short v237, v112, s[4:5]
	s_add_u32 s4, s4, 0x800
	s_addc_u32 s5, s5, 0
	global_store_short v237, v113, s[4:5]
	s_add_u32 s4, s4, 0x800
	s_addc_u32 s5, s5, 0
	global_store_short v237, v114, s[4:5]
	s_add_u32 s4, s4, 0x800
	s_addc_u32 s5, s5, 0
	global_store_short v237, v115, s[4:5]
	s_add_u32 s4, s4, 0x800
	s_addc_u32 s5, s5, 0
	global_store_short v237, v116, s[4:5]
	s_add_u32 s4, s4, 0x800
	s_addc_u32 s5, s5, 0
	global_store_short v237, v117, s[4:5]
	s_add_u32 s4, s4, 0x800
	s_addc_u32 s5, s5, 0
	global_store_short v237, v118, s[4:5]
	s_add_u32 s4, s4, 0x800
	s_addc_u32 s5, s5, 0
	global_store_short v237, v119, s[4:5]
	s_add_u32 s4, s4, 0x800
	s_addc_u32 s5, s5, 0
	global_store_short v237, v120, s[4:5]
	s_add_u32 s4, s4, 0x800
	s_addc_u32 s5, s5, 0
	global_store_short v237, v121, s[4:5]
	v_add_u32_e32 v89, s62, v89
	v_add_u32_e32 v130, s62, v130
	v_add_u32_e32 v131, s62, v131
	v_add_u32_e32 v133, s62, v133
	s_sub_u32 s62, 0, s62
	s_add_u32 s69, s69, 1
	s_cmp_lt_u32 s69, s70
	s_cbranch_scc1 .Lmy_lrub_tile
	s_waitcnt lgkmcnt(0)
	s_barrier
	s_branch .LBB0_680
